# GEMM K-loops: one vmcnt(16) wait per LDS write group instead of four counted waits
# speedup vs baseline: 1.1509x; 1.0029x over previous
; #define GLOAD(RA, RB, kt) { _Pragma("unroll") for (int i = 0; i < 8; ++i) { const int ia = (tail && i >= 4) ? i - 4 : i; \
;     RA[i] = *(const u32x4*)(abase + ((size_t)(32 * ia) * lda + (kt) * 64) * 2 + aoff); RB[i] = *(const u32x4*)(bbase + ((size_t)(32 * i) * K + (kt) * 64) * 2 + boff); } }
; #define LWRITE(RA, RB, buf) { char* as_ = lds + (buf) * 2 * G_TILE; char* bs_ = as_ + G_TILE; _Pragma("unroll") for (int i = 0; i < 8; ++i) { *(u32x4*)(as_ + (lrow + 32 * i) * GS_B + lch * 16) = RA[i]; *(u32x4*)(bs_ + (lrow + 32 * i) * GS_B + lch * 16) = RB[i]; } }
; template <int EPI>
; DEV void gemm_tile(CParams& p, int layer, const bf16_t* __restrict__ A, int lda, const bf16_t* __restrict__ Bt, int K, int m0, int n0, int nt, char* lds, const int swave) {
;     ...
;   const char* asr = lds + (wm * 128 + lr) * GS_B + hh * 16;
;   const char* bsr = lds + G_TILE + (wn * 128 + lr) * GS_B + hh * 16;
;   char* wsw = lds + lrow * GS_B + lch * 16;
;     ...
;   GLOAD(ra0, rb0, 0); GLOAD(ra1, rb1, 1); LWRITE(ra0, rb0, 0); __syncthreads();
; #pragma unroll 1
;   for (int kt = 0; kt < nk; kt += 2) {
;     if (kt + 2 < nk) GLOAD(ra0, rb0, kt + 2);
;     COMPUTE(0, ra1, rb1, 1, true);
;     __syncthreads();
.LBB0_101:
	s_cmp_eq_u32 s36, 0
	s_cbranch_scc0 .Lzi_i1
	ds_read_b128 v[188:191], v49
	ds_read_b128 v[192:195], v49 offset:4608
	ds_read_b128 v[196:199], v49 offset:9216
	ds_read_b128 v[200:203], v49 offset:13824
	ds_read_b128 v[184:187], v48
	ds_read_b128 v[204:207], v48 offset:4608
	s_waitcnt lgkmcnt(1)
	v_mfma_f32_32x32x16_bf16 a[192:207], v[184:187], v[188:191], 0
	v_mfma_f32_32x32x16_bf16 a[128:143], v[184:187], v[192:195], 0
	v_mfma_f32_32x32x16_bf16 a[64:79], v[184:187], v[196:199], 0
	v_mfma_f32_32x32x16_bf16 a[0:15], v[184:187], v[200:203], 0
	ds_read_b128 v[184:187], v48 offset:9216
	ds_read_b128 v[208:211], v49 offset:32
	ds_read_b128 v[212:215], v49 offset:4640
	v_lshl_add_u64 v[50:51], v[0:1], 0, s[34:35]
	global_load_dwordx4 v[52:55], v[50:51], off
	s_waitcnt lgkmcnt(3)
	v_mfma_f32_32x32x16_bf16 a[208:223], v[204:207], v[188:191], 0
	v_mfma_f32_32x32x16_bf16 a[144:159], v[204:207], v[192:195], 0
	v_mfma_f32_32x32x16_bf16 a[80:95], v[204:207], v[196:199], 0
	v_mfma_f32_32x32x16_bf16 a[16:31], v[204:207], v[200:203], 0
	ds_read_b128 v[204:207], v48 offset:13824
	ds_read_b128 v[216:219], v49 offset:9248
	ds_read_b128 v[220:223], v49 offset:13856
	v_lshl_add_u64 v[50:51], v[2:3], 0, s[34:35]
	s_or_b32 s2, s34, 0x10000
	s_mov_b32 s3, s35
	global_load_dwordx4 v[56:59], v[50:51], off
	s_waitcnt lgkmcnt(5)
	v_mfma_f32_32x32x16_bf16 a[224:239], v[184:187], v[188:191], 0
	v_mfma_f32_32x32x16_bf16 a[160:175], v[184:187], v[192:195], 0
	v_mfma_f32_32x32x16_bf16 a[96:111], v[184:187], v[196:199], 0
	v_mfma_f32_32x32x16_bf16 a[32:47], v[184:187], v[200:203], 0
	ds_read_b128 v[184:187], v48 offset:32
	v_lshl_add_u64 v[50:51], v[0:1], 0, s[2:3]
	global_load_dwordx4 v[60:63], v[50:51], off
	s_waitcnt lgkmcnt(3)
	v_mfma_f32_32x32x16_bf16 a[240:255], v[204:207], v[188:191], 0
	v_mfma_f32_32x32x16_bf16 a[176:191], v[204:207], v[192:195], 0
	v_mfma_f32_32x32x16_bf16 a[112:127], v[204:207], v[196:199], 0
	v_mfma_f32_32x32x16_bf16 a[48:63], v[204:207], v[200:203], 0
	ds_read_b128 v[204:207], v48 offset:4640
	v_lshl_add_u64 v[50:51], v[2:3], 0, s[2:3]
	s_or_b32 s2, s34, 0x20000
	global_load_dwordx4 v[68:71], v[50:51], off
	s_waitcnt vmcnt(16)
	ds_write_b128 v31, v[100:103]
	ds_write_b128 v32, v[104:107]
	ds_write_b128 v41, v[112:115]
	ds_write_b128 v42, v[116:119]
	s_waitcnt lgkmcnt(5)
	v_mfma_f32_32x32x16_bf16 a[192:207], v[184:187], v[208:211], a[192:207]
	v_mfma_f32_32x32x16_bf16 a[128:143], v[184:187], v[212:215], a[128:143]
	v_mfma_f32_32x32x16_bf16 a[64:79], v[184:187], v[216:219], a[64:79]
	v_mfma_f32_32x32x16_bf16 a[0:15], v[184:187], v[220:223], a[0:15]
	ds_read_b128 v[184:187], v48 offset:9248
	ds_read_b128 v[188:191], v49 offset:64
	ds_read_b128 v[192:195], v49 offset:4672
	v_lshl_add_u64 v[50:51], v[0:1], 0, s[2:3]
	global_load_dwordx4 v[72:75], v[50:51], off
	s_waitcnt lgkmcnt(7)
	v_mfma_f32_32x32x16_bf16 a[208:223], v[204:207], v[208:211], a[208:223]
	v_mfma_f32_32x32x16_bf16 a[144:159], v[204:207], v[212:215], a[144:159]
	v_mfma_f32_32x32x16_bf16 a[80:95], v[204:207], v[216:219], a[80:95]
	v_mfma_f32_32x32x16_bf16 a[16:31], v[204:207], v[220:223], a[16:31]
	ds_read_b128 v[204:207], v48 offset:13856
	ds_read_b128 v[196:199], v49 offset:9280
	ds_read_b128 v[200:203], v49 offset:13888
	v_lshl_add_u64 v[50:51], v[2:3], 0, s[2:3]
	s_or_b32 s2, s34, 0x30000
	global_load_dwordx4 v[76:79], v[50:51], off
	s_waitcnt lgkmcnt(5)
	v_mfma_f32_32x32x16_bf16 a[224:239], v[184:187], v[208:211], a[224:239]
	v_mfma_f32_32x32x16_bf16 a[160:175], v[184:187], v[212:215], a[160:175]
	v_mfma_f32_32x32x16_bf16 a[96:111], v[184:187], v[216:219], a[96:111]
	v_mfma_f32_32x32x16_bf16 a[32:47], v[184:187], v[220:223], a[32:47]
	ds_read_b128 v[184:187], v48 offset:64
	v_lshl_add_u64 v[50:51], v[0:1], 0, s[2:3]
	global_load_dwordx4 v[80:83], v[50:51], off
	s_waitcnt lgkmcnt(3)
	v_mfma_f32_32x32x16_bf16 a[240:255], v[204:207], v[208:211], a[240:255]
	v_mfma_f32_32x32x16_bf16 a[176:191], v[204:207], v[212:215], a[176:191]
	v_mfma_f32_32x32x16_bf16 a[112:127], v[204:207], v[216:219], a[112:127]
	v_mfma_f32_32x32x16_bf16 a[48:63], v[204:207], v[220:223], a[48:63]
	ds_read_b128 v[204:207], v48 offset:4672
	v_lshl_add_u64 v[50:51], v[2:3], 0, s[2:3]
	s_or_b32 s2, s34, 0x40000
	global_load_dwordx4 v[84:87], v[50:51], off
	s_waitcnt vmcnt(16)
	ds_write_b128 v37, v[120:123]
	ds_write_b128 v38, v[128:131]
	ds_write_b128 v39, v[132:135]
	ds_write_b128 v40, v[136:139]
	s_waitcnt lgkmcnt(5)
	v_mfma_f32_32x32x16_bf16 a[192:207], v[184:187], v[188:191], a[192:207]
	v_mfma_f32_32x32x16_bf16 a[128:143], v[184:187], v[192:195], a[128:143]
	v_mfma_f32_32x32x16_bf16 a[64:79], v[184:187], v[196:199], a[64:79]
	v_mfma_f32_32x32x16_bf16 a[0:15], v[184:187], v[200:203], a[0:15]
	ds_read_b128 v[184:187], v48 offset:9280
	ds_read_b128 v[208:211], v49 offset:96
	ds_read_b128 v[212:215], v49 offset:4704
	v_lshl_add_u64 v[50:51], v[0:1], 0, s[2:3]
	global_load_dwordx4 v[88:91], v[50:51], off
	s_waitcnt lgkmcnt(7)
	v_mfma_f32_32x32x16_bf16 a[208:223], v[204:207], v[188:191], a[208:223]
	v_mfma_f32_32x32x16_bf16 a[144:159], v[204:207], v[192:195], a[144:159]
	v_mfma_f32_32x32x16_bf16 a[80:95], v[204:207], v[196:199], a[80:95]
	v_mfma_f32_32x32x16_bf16 a[16:31], v[204:207], v[200:203], a[16:31]
	ds_read_b128 v[204:207], v48 offset:13888
	ds_read_b128 v[216:219], v49 offset:9312
	ds_read_b128 v[220:223], v49 offset:13920
	v_lshl_add_u64 v[50:51], v[2:3], 0, s[2:3]
	s_or_b32 s2, s34, 0x50000
	global_load_dwordx4 v[92:95], v[50:51], off
	s_waitcnt lgkmcnt(5)
; #define GLOAD(RA, RB, kt) { _Pragma("unroll") for (int i = 0; i < 8; ++i) { const int ia = (tail && i >= 4) ? i - 4 : i; \
;     RA[i] = *(const u32x4*)(abase + ((size_t)(32 * ia) * lda + (kt) * 64) * 2 + aoff); RB[i] = *(const u32x4*)(bbase + ((size_t)(32 * i) * K + (kt) * 64) * 2 + boff); } }
; #define LWRITE(RA, RB, buf) { char* as_ = lds + (buf) * 2 * G_TILE; char* bs_ = as_ + G_TILE; _Pragma("unroll") for (int i = 0; i < 8; ++i) { *(u32x4*)(as_ + (lrow + 32 * i) * GS_B + lch * 16) = RA[i]; *(u32x4*)(bs_ + (lrow + 32 * i) * GS_B + lch * 16) = RB[i]; } }
; template <int EPI>
; DEV void gemm_tile(CParams& p, int layer, const bf16_t* __restrict__ A, int lda, const bf16_t* __restrict__ Bt, int K, int m0, int n0, int nt, char* lds, const int swave) {
;     ...
;   GLOAD(ra0, rb0, 0); GLOAD(ra1, rb1, 1); LWRITE(ra0, rb0, 0); __syncthreads();
; #pragma unroll 1
;   for (int kt = 0; kt < nk; kt += 2) {
;     if (kt + 2 < nk) GLOAD(ra0, rb0, kt + 2);
;     COMPUTE(0, ra1, rb1, 1, true);
;     __syncthreads();
;     const bool more = kt + 2 < nk;
;     if (kt + 3 < nk) GLOAD(ra1, rb1, kt + 3);
;     COMPUTE(1, ra0, rb0, 0, more);
	v_mfma_f32_32x32x16_bf16 a[224:239], v[184:187], v[188:191], a[224:239]
	v_mfma_f32_32x32x16_bf16 a[160:175], v[184:187], v[192:195], a[160:175]
	v_mfma_f32_32x32x16_bf16 a[96:111], v[184:187], v[196:199], a[96:111]
	v_mfma_f32_32x32x16_bf16 a[32:47], v[184:187], v[200:203], a[32:47]
	ds_read_b128 v[184:187], v48 offset:96
	v_lshl_add_u64 v[50:51], v[0:1], 0, s[2:3]
	global_load_dwordx4 v[96:99], v[50:51], off
	s_waitcnt lgkmcnt(3)
	v_mfma_f32_32x32x16_bf16 a[240:255], v[204:207], v[188:191], a[240:255]
	v_mfma_f32_32x32x16_bf16 a[176:191], v[204:207], v[192:195], a[176:191]
	v_mfma_f32_32x32x16_bf16 a[112:127], v[204:207], v[196:199], a[112:127]
	v_mfma_f32_32x32x16_bf16 a[48:63], v[204:207], v[200:203], a[48:63]
	ds_read_b128 v[204:207], v48 offset:4704
	v_lshl_add_u64 v[50:51], v[2:3], 0, s[2:3]
	s_or_b32 s2, s34, 0x60000
	global_load_dwordx4 v[108:111], v[50:51], off
	s_waitcnt vmcnt(16)
	ds_write_b128 v33, v[140:143]
	ds_write_b128 v34, v[148:151]
	ds_write_b128 v35, v[152:155]
	ds_write_b128 v36, v[156:159]
	s_waitcnt lgkmcnt(5)
	v_mfma_f32_32x32x16_bf16 a[192:207], v[184:187], v[208:211], a[192:207]
	v_mfma_f32_32x32x16_bf16 a[128:143], v[184:187], v[212:215], a[128:143]
	v_mfma_f32_32x32x16_bf16 a[64:79], v[184:187], v[216:219], a[64:79]
	v_mfma_f32_32x32x16_bf16 a[0:15], v[184:187], v[220:223], a[0:15]
	ds_read_b128 v[184:187], v48 offset:9312
	v_lshl_add_u64 v[50:51], v[0:1], 0, s[2:3]
	global_load_dwordx4 v[124:127], v[50:51], off
	s_waitcnt lgkmcnt(5)
	v_mfma_f32_32x32x16_bf16 a[208:223], v[204:207], v[208:211], a[208:223]
	v_mfma_f32_32x32x16_bf16 a[144:159], v[204:207], v[212:215], a[144:159]
	v_mfma_f32_32x32x16_bf16 a[80:95], v[204:207], v[216:219], a[80:95]
	v_mfma_f32_32x32x16_bf16 a[16:31], v[204:207], v[220:223], a[16:31]
	ds_read_b128 v[204:207], v48 offset:13920
	v_lshl_add_u64 v[50:51], v[2:3], 0, s[2:3]
	s_or_b32 s34, s34, 0x70000
	global_load_dwordx4 v[144:147], v[50:51], off
	s_waitcnt lgkmcnt(1)
	v_mfma_f32_32x32x16_bf16 a[224:239], v[184:187], v[208:211], a[224:239]
	v_mfma_f32_32x32x16_bf16 a[160:175], v[184:187], v[212:215], a[160:175]
	v_mfma_f32_32x32x16_bf16 a[96:111], v[184:187], v[216:219], a[96:111]
	v_mfma_f32_32x32x16_bf16 a[32:47], v[184:187], v[220:223], a[32:47]
	v_lshl_add_u64 v[50:51], v[0:1], 0, s[34:35]
	global_load_dwordx4 v[160:163], v[50:51], off
	s_waitcnt lgkmcnt(0)
	v_mfma_f32_32x32x16_bf16 a[240:255], v[204:207], v[208:211], a[240:255]
	v_mfma_f32_32x32x16_bf16 a[176:191], v[204:207], v[212:215], a[176:191]
	v_mfma_f32_32x32x16_bf16 a[112:127], v[204:207], v[216:219], a[112:127]
	v_mfma_f32_32x32x16_bf16 a[48:63], v[204:207], v[220:223], a[48:63]
	v_lshl_add_u64 v[50:51], v[2:3], 0, s[34:35]
	global_load_dwordx4 v[180:183], v[50:51], off
	s_waitcnt vmcnt(16)
	ds_write_b128 v43, v[164:167]
	ds_write_b128 v44, v[168:171]
	ds_write_b128 v45, v[172:175]
	ds_write_b128 v46, v[176:179]
	s_branch .LBB0_117
.Lzi_i1:
	ds_read_b128 v[188:191], v49
	ds_read_b128 v[192:195], v49 offset:4608
	ds_read_b128 v[196:199], v49 offset:9216
	ds_read_b128 v[200:203], v49 offset:13824
	ds_read_b128 v[184:187], v48
	ds_read_b128 v[204:207], v48 offset:4608
	s_waitcnt lgkmcnt(1)
	v_mfma_f32_32x32x16_bf16 a[192:207], v[184:187], v[188:191], a[192:207]
	v_mfma_f32_32x32x16_bf16 a[128:143], v[184:187], v[192:195], a[128:143]
	v_mfma_f32_32x32x16_bf16 a[64:79], v[184:187], v[196:199], a[64:79]
	v_mfma_f32_32x32x16_bf16 a[0:15], v[184:187], v[200:203], a[0:15]
	ds_read_b128 v[184:187], v48 offset:9216
	ds_read_b128 v[208:211], v49 offset:32
	ds_read_b128 v[212:215], v49 offset:4640
	v_lshl_add_u64 v[50:51], v[0:1], 0, s[34:35]
	global_load_dwordx4 v[52:55], v[50:51], off
	s_waitcnt lgkmcnt(3)
	v_mfma_f32_32x32x16_bf16 a[208:223], v[204:207], v[188:191], a[208:223]
	v_mfma_f32_32x32x16_bf16 a[144:159], v[204:207], v[192:195], a[144:159]
	v_mfma_f32_32x32x16_bf16 a[80:95], v[204:207], v[196:199], a[80:95]
	v_mfma_f32_32x32x16_bf16 a[16:31], v[204:207], v[200:203], a[16:31]
	ds_read_b128 v[204:207], v48 offset:13824
	ds_read_b128 v[216:219], v49 offset:9248
	ds_read_b128 v[220:223], v49 offset:13856
	v_lshl_add_u64 v[50:51], v[2:3], 0, s[34:35]
	s_or_b32 s2, s34, 0x10000
	s_mov_b32 s3, s35
	global_load_dwordx4 v[56:59], v[50:51], off
	s_waitcnt lgkmcnt(5)
	v_mfma_f32_32x32x16_bf16 a[224:239], v[184:187], v[188:191], a[224:239]
	v_mfma_f32_32x32x16_bf16 a[160:175], v[184:187], v[192:195], a[160:175]
	v_mfma_f32_32x32x16_bf16 a[96:111], v[184:187], v[196:199], a[96:111]
	v_mfma_f32_32x32x16_bf16 a[32:47], v[184:187], v[200:203], a[32:47]
	ds_read_b128 v[184:187], v48 offset:32
	v_lshl_add_u64 v[50:51], v[0:1], 0, s[2:3]
	global_load_dwordx4 v[60:63], v[50:51], off
	s_waitcnt lgkmcnt(3)
	v_mfma_f32_32x32x16_bf16 a[240:255], v[204:207], v[188:191], a[240:255]
	v_mfma_f32_32x32x16_bf16 a[176:191], v[204:207], v[192:195], a[176:191]
	v_mfma_f32_32x32x16_bf16 a[112:127], v[204:207], v[196:199], a[112:127]
	v_mfma_f32_32x32x16_bf16 a[48:63], v[204:207], v[200:203], a[48:63]
	ds_read_b128 v[204:207], v48 offset:4640
	v_lshl_add_u64 v[50:51], v[2:3], 0, s[2:3]
	s_or_b32 s2, s34, 0x20000
	global_load_dwordx4 v[68:71], v[50:51], off
	s_waitcnt vmcnt(16)
	ds_write_b128 v31, v[100:103]
	ds_write_b128 v32, v[104:107]
	ds_write_b128 v41, v[112:115]
	ds_write_b128 v42, v[116:119]
	s_waitcnt lgkmcnt(5)
	v_mfma_f32_32x32x16_bf16 a[192:207], v[184:187], v[208:211], a[192:207]
	v_mfma_f32_32x32x16_bf16 a[128:143], v[184:187], v[212:215], a[128:143]
	v_mfma_f32_32x32x16_bf16 a[64:79], v[184:187], v[216:219], a[64:79]
	v_mfma_f32_32x32x16_bf16 a[0:15], v[184:187], v[220:223], a[0:15]
	ds_read_b128 v[184:187], v48 offset:9248
	ds_read_b128 v[188:191], v49 offset:64
	ds_read_b128 v[192:195], v49 offset:4672
	v_lshl_add_u64 v[50:51], v[0:1], 0, s[2:3]
	global_load_dwordx4 v[72:75], v[50:51], off
	s_waitcnt lgkmcnt(7)
; #define GLOAD(RA, RB, kt) { _Pragma("unroll") for (int i = 0; i < 8; ++i) { const int ia = (tail && i >= 4) ? i - 4 : i; \
;     RA[i] = *(const u32x4*)(abase + ((size_t)(32 * ia) * lda + (kt) * 64) * 2 + aoff); RB[i] = *(const u32x4*)(bbase + ((size_t)(32 * i) * K + (kt) * 64) * 2 + boff); } }
; #define LWRITE(RA, RB, buf) { char* as_ = lds + (buf) * 2 * G_TILE; char* bs_ = as_ + G_TILE; _Pragma("unroll") for (int i = 0; i < 8; ++i) { *(u32x4*)(as_ + (lrow + 32 * i) * GS_B + lch * 16) = RA[i]; *(u32x4*)(bs_ + (lrow + 32 * i) * GS_B + lch * 16) = RB[i]; } }
; template <int EPI>
; DEV void gemm_tile(CParams& p, int layer, const bf16_t* __restrict__ A, int lda, const bf16_t* __restrict__ Bt, int K, int m0, int n0, int nt, char* lds, const int swave) {
;     ...
;   GLOAD(ra0, rb0, 0); GLOAD(ra1, rb1, 1); LWRITE(ra0, rb0, 0); __syncthreads();
; #pragma unroll 1
;   for (int kt = 0; kt < nk; kt += 2) {
;     if (kt + 2 < nk) GLOAD(ra0, rb0, kt + 2);
;     COMPUTE(0, ra1, rb1, 1, true);
;     __syncthreads();
;     const bool more = kt + 2 < nk;
;     if (kt + 3 < nk) GLOAD(ra1, rb1, kt + 3);
;     COMPUTE(1, ra0, rb0, 0, more);
	v_mfma_f32_32x32x16_bf16 a[208:223], v[204:207], v[208:211], a[208:223]
	v_mfma_f32_32x32x16_bf16 a[144:159], v[204:207], v[212:215], a[144:159]
	v_mfma_f32_32x32x16_bf16 a[80:95], v[204:207], v[216:219], a[80:95]
	v_mfma_f32_32x32x16_bf16 a[16:31], v[204:207], v[220:223], a[16:31]
	ds_read_b128 v[204:207], v48 offset:13856
	ds_read_b128 v[196:199], v49 offset:9280
	ds_read_b128 v[200:203], v49 offset:13888
	v_lshl_add_u64 v[50:51], v[2:3], 0, s[2:3]
	s_or_b32 s2, s34, 0x30000
	global_load_dwordx4 v[76:79], v[50:51], off
	s_waitcnt lgkmcnt(5)
	v_mfma_f32_32x32x16_bf16 a[224:239], v[184:187], v[208:211], a[224:239]
	v_mfma_f32_32x32x16_bf16 a[160:175], v[184:187], v[212:215], a[160:175]
	v_mfma_f32_32x32x16_bf16 a[96:111], v[184:187], v[216:219], a[96:111]
	v_mfma_f32_32x32x16_bf16 a[32:47], v[184:187], v[220:223], a[32:47]
	ds_read_b128 v[184:187], v48 offset:64
	v_lshl_add_u64 v[50:51], v[0:1], 0, s[2:3]
	global_load_dwordx4 v[80:83], v[50:51], off
	s_waitcnt lgkmcnt(3)
	v_mfma_f32_32x32x16_bf16 a[240:255], v[204:207], v[208:211], a[240:255]
	v_mfma_f32_32x32x16_bf16 a[176:191], v[204:207], v[212:215], a[176:191]
	v_mfma_f32_32x32x16_bf16 a[112:127], v[204:207], v[216:219], a[112:127]
	v_mfma_f32_32x32x16_bf16 a[48:63], v[204:207], v[220:223], a[48:63]
	ds_read_b128 v[204:207], v48 offset:4672
	v_lshl_add_u64 v[50:51], v[2:3], 0, s[2:3]
	s_or_b32 s2, s34, 0x40000
	global_load_dwordx4 v[84:87], v[50:51], off
	s_waitcnt vmcnt(16)
	ds_write_b128 v37, v[120:123]
	ds_write_b128 v38, v[128:131]
	ds_write_b128 v39, v[132:135]
	ds_write_b128 v40, v[136:139]
	s_waitcnt lgkmcnt(5)
	v_mfma_f32_32x32x16_bf16 a[192:207], v[184:187], v[188:191], a[192:207]
	v_mfma_f32_32x32x16_bf16 a[128:143], v[184:187], v[192:195], a[128:143]
	v_mfma_f32_32x32x16_bf16 a[64:79], v[184:187], v[196:199], a[64:79]
	v_mfma_f32_32x32x16_bf16 a[0:15], v[184:187], v[200:203], a[0:15]
	ds_read_b128 v[184:187], v48 offset:9280
	ds_read_b128 v[208:211], v49 offset:96
	ds_read_b128 v[212:215], v49 offset:4704
	v_lshl_add_u64 v[50:51], v[0:1], 0, s[2:3]
	global_load_dwordx4 v[88:91], v[50:51], off
	s_waitcnt lgkmcnt(7)
	v_mfma_f32_32x32x16_bf16 a[208:223], v[204:207], v[188:191], a[208:223]
	v_mfma_f32_32x32x16_bf16 a[144:159], v[204:207], v[192:195], a[144:159]
	v_mfma_f32_32x32x16_bf16 a[80:95], v[204:207], v[196:199], a[80:95]
	v_mfma_f32_32x32x16_bf16 a[16:31], v[204:207], v[200:203], a[16:31]
	ds_read_b128 v[204:207], v48 offset:13888
	ds_read_b128 v[216:219], v49 offset:9312
	ds_read_b128 v[220:223], v49 offset:13920
	v_lshl_add_u64 v[50:51], v[2:3], 0, s[2:3]
	s_or_b32 s2, s34, 0x50000
	global_load_dwordx4 v[92:95], v[50:51], off
	s_waitcnt lgkmcnt(5)
	v_mfma_f32_32x32x16_bf16 a[224:239], v[184:187], v[188:191], a[224:239]
	v_mfma_f32_32x32x16_bf16 a[160:175], v[184:187], v[192:195], a[160:175]
	v_mfma_f32_32x32x16_bf16 a[96:111], v[184:187], v[196:199], a[96:111]
	v_mfma_f32_32x32x16_bf16 a[32:47], v[184:187], v[200:203], a[32:47]
	ds_read_b128 v[184:187], v48 offset:96
	v_lshl_add_u64 v[50:51], v[0:1], 0, s[2:3]
	global_load_dwordx4 v[96:99], v[50:51], off
	s_waitcnt lgkmcnt(3)
	v_mfma_f32_32x32x16_bf16 a[240:255], v[204:207], v[188:191], a[240:255]
	v_mfma_f32_32x32x16_bf16 a[176:191], v[204:207], v[192:195], a[176:191]
	v_mfma_f32_32x32x16_bf16 a[112:127], v[204:207], v[196:199], a[112:127]
	v_mfma_f32_32x32x16_bf16 a[48:63], v[204:207], v[200:203], a[48:63]
	ds_read_b128 v[204:207], v48 offset:4704
	v_lshl_add_u64 v[50:51], v[2:3], 0, s[2:3]
	s_or_b32 s2, s34, 0x60000
	global_load_dwordx4 v[108:111], v[50:51], off
	s_waitcnt vmcnt(16)
	ds_write_b128 v33, v[140:143]
	ds_write_b128 v34, v[148:151]
	ds_write_b128 v35, v[152:155]
	ds_write_b128 v36, v[156:159]
	s_waitcnt lgkmcnt(5)
	v_mfma_f32_32x32x16_bf16 a[192:207], v[184:187], v[208:211], a[192:207]
	v_mfma_f32_32x32x16_bf16 a[128:143], v[184:187], v[212:215], a[128:143]
	v_mfma_f32_32x32x16_bf16 a[64:79], v[184:187], v[216:219], a[64:79]
	v_mfma_f32_32x32x16_bf16 a[0:15], v[184:187], v[220:223], a[0:15]
	ds_read_b128 v[184:187], v48 offset:9312
	v_lshl_add_u64 v[50:51], v[0:1], 0, s[2:3]
	global_load_dwordx4 v[124:127], v[50:51], off
	s_waitcnt lgkmcnt(5)
	v_mfma_f32_32x32x16_bf16 a[208:223], v[204:207], v[208:211], a[208:223]
	v_mfma_f32_32x32x16_bf16 a[144:159], v[204:207], v[212:215], a[144:159]
	v_mfma_f32_32x32x16_bf16 a[80:95], v[204:207], v[216:219], a[80:95]
	v_mfma_f32_32x32x16_bf16 a[16:31], v[204:207], v[220:223], a[16:31]
	ds_read_b128 v[204:207], v48 offset:13920
	v_lshl_add_u64 v[50:51], v[2:3], 0, s[2:3]
	s_or_b32 s34, s34, 0x70000
	global_load_dwordx4 v[144:147], v[50:51], off
	s_waitcnt lgkmcnt(1)
	v_mfma_f32_32x32x16_bf16 a[224:239], v[184:187], v[208:211], a[224:239]
	v_mfma_f32_32x32x16_bf16 a[160:175], v[184:187], v[212:215], a[160:175]
	v_mfma_f32_32x32x16_bf16 a[96:111], v[184:187], v[216:219], a[96:111]
	v_mfma_f32_32x32x16_bf16 a[32:47], v[184:187], v[220:223], a[32:47]
	v_lshl_add_u64 v[50:51], v[0:1], 0, s[34:35]
	global_load_dwordx4 v[160:163], v[50:51], off
	s_waitcnt lgkmcnt(0)
	v_mfma_f32_32x32x16_bf16 a[240:255], v[204:207], v[208:211], a[240:255]
	v_mfma_f32_32x32x16_bf16 a[176:191], v[204:207], v[212:215], a[176:191]
	v_mfma_f32_32x32x16_bf16 a[112:127], v[204:207], v[216:219], a[112:127]
	v_mfma_f32_32x32x16_bf16 a[48:63], v[204:207], v[220:223], a[48:63]
	v_lshl_add_u64 v[50:51], v[2:3], 0, s[34:35]
	global_load_dwordx4 v[180:183], v[50:51], off
	s_waitcnt vmcnt(16)
	ds_write_b128 v43, v[164:167]
	ds_write_b128 v44, v[168:171]
	ds_write_b128 v45, v[172:175]
	ds_write_b128 v46, v[176:179]

; #define GLOAD(RA, RB, kt) { _Pragma("unroll") for (int i = 0; i < 8; ++i) { const int ia = (tail && i >= 4) ? i - 4 : i; \
;     RA[i] = *(const u32x4*)(abase + ((size_t)(32 * ia) * lda + (kt) * 64) * 2 + aoff); RB[i] = *(const u32x4*)(bbase + ((size_t)(32 * i) * K + (kt) * 64) * 2 + boff); } }
; #define LWRITE(RA, RB, buf) { char* as_ = lds + (buf) * 2 * G_TILE; char* bs_ = as_ + G_TILE; _Pragma("unroll") for (int i = 0; i < 8; ++i) { *(u32x4*)(as_ + (lrow + 32 * i) * GS_B + lch * 16) = RA[i]; *(u32x4*)(bs_ + (lrow + 32 * i) * GS_B + lch * 16) = RB[i]; } }
; template <int EPI>
; DEV void gemm_tile(CParams& p, int layer, const bf16_t* __restrict__ A, int lda, const bf16_t* __restrict__ Bt, int K, int m0, int n0, int nt, char* lds, const int swave) {
;     ...
;   GLOAD(ra0, rb0, 0); GLOAD(ra1, rb1, 1); LWRITE(ra0, rb0, 0); __syncthreads();
; #pragma unroll 1
;   for (int kt = 0; kt < nk; kt += 2) {
;     if (kt + 2 < nk) GLOAD(ra0, rb0, kt + 2);
;     COMPUTE(0, ra1, rb1, 1, true);
;     __syncthreads();
;     const bool more = kt + 2 < nk;
;     if (kt + 3 < nk) GLOAD(ra1, rb1, kt + 3);
;     COMPUTE(1, ra0, rb0, 0, more);
.LBB0_119:
	v_add_u32_e32 v224, 0x1b000, v29
	v_add_u32_e32 v225, 0x12000, v49
	s_andn2_b64 vcc, exec, s[60:61]
	s_cbranch_vccnz .Lpg_i1_nomore
	ds_read_b128 v[188:191], v225
	ds_read_b128 v[192:195], v225 offset:4608
	ds_read_b128 v[196:199], v225 offset:9216
	ds_read_b128 v[200:203], v225 offset:13824
	ds_read_b128 v[184:187], v224
	ds_read_b128 v[204:207], v224 offset:4608
	s_waitcnt lgkmcnt(1)
	v_mfma_f32_32x32x16_bf16 a[192:207], v[184:187], v[188:191], a[192:207]
	v_mfma_f32_32x32x16_bf16 a[128:143], v[184:187], v[192:195], a[128:143]
	v_mfma_f32_32x32x16_bf16 a[64:79], v[184:187], v[196:199], a[64:79]
	v_mfma_f32_32x32x16_bf16 a[0:15], v[184:187], v[200:203], a[0:15]
	ds_read_b128 v[184:187], v224 offset:9216
	ds_read_b128 v[208:211], v225 offset:32
	ds_read_b128 v[212:215], v225 offset:4640
	s_lshl_b32 s34, s36, 7
	v_lshl_add_u64 v[50:51], v[0:1], 0, s[34:35]
	v_lshl_add_u64 v[64:65], v[2:3], 0, s[34:35]
	global_load_dwordx4 v[100:103], v[50:51], off offset:384
	s_waitcnt lgkmcnt(3)
	v_mfma_f32_32x32x16_bf16 a[208:223], v[204:207], v[188:191], a[208:223]
	v_mfma_f32_32x32x16_bf16 a[144:159], v[204:207], v[192:195], a[144:159]
	v_mfma_f32_32x32x16_bf16 a[80:95], v[204:207], v[196:199], a[80:95]
	v_mfma_f32_32x32x16_bf16 a[16:31], v[204:207], v[200:203], a[16:31]
	ds_read_b128 v[204:207], v224 offset:13824
	ds_read_b128 v[216:219], v225 offset:9248
	ds_read_b128 v[220:223], v225 offset:13856
	global_load_dwordx4 v[104:107], v[64:65], off offset:384
	s_waitcnt lgkmcnt(5)
	v_mfma_f32_32x32x16_bf16 a[224:239], v[184:187], v[188:191], a[224:239]
	v_mfma_f32_32x32x16_bf16 a[160:175], v[184:187], v[192:195], a[160:175]
	v_mfma_f32_32x32x16_bf16 a[96:111], v[184:187], v[196:199], a[96:111]
	v_mfma_f32_32x32x16_bf16 a[32:47], v[184:187], v[200:203], a[32:47]
	ds_read_b128 v[184:187], v224 offset:32
	v_add_co_u32_e32 v50, vcc, 0x10000, v50
	s_nop 1
	v_addc_co_u32_e32 v51, vcc, 0, v51, vcc
	v_add_co_u32_e32 v64, vcc, 0x10000, v64
	s_nop 1
	v_addc_co_u32_e32 v65, vcc, 0, v65, vcc
	global_load_dwordx4 v[112:115], v[50:51], off offset:384
	s_waitcnt lgkmcnt(3)
	v_mfma_f32_32x32x16_bf16 a[240:255], v[204:207], v[188:191], a[240:255]
	v_mfma_f32_32x32x16_bf16 a[176:191], v[204:207], v[192:195], a[176:191]
	v_mfma_f32_32x32x16_bf16 a[112:127], v[204:207], v[196:199], a[112:127]
	v_mfma_f32_32x32x16_bf16 a[48:63], v[204:207], v[200:203], a[48:63]
	ds_read_b128 v[204:207], v224 offset:4640
	global_load_dwordx4 v[116:119], v[64:65], off offset:384
	s_waitcnt vmcnt(16)
	ds_write_b128 v30, v[52:55]
	ds_write_b128 v30, v[56:59] offset:36864
	ds_write_b128 v30, v[60:63] offset:4608
	ds_write_b128 v30, v[68:71] offset:41472
	s_waitcnt lgkmcnt(5)
	v_mfma_f32_32x32x16_bf16 a[192:207], v[184:187], v[208:211], a[192:207]
	v_mfma_f32_32x32x16_bf16 a[128:143], v[184:187], v[212:215], a[128:143]
	v_mfma_f32_32x32x16_bf16 a[64:79], v[184:187], v[216:219], a[64:79]
	v_mfma_f32_32x32x16_bf16 a[0:15], v[184:187], v[220:223], a[0:15]
	ds_read_b128 v[184:187], v224 offset:9248
	ds_read_b128 v[188:191], v225 offset:64
	ds_read_b128 v[192:195], v225 offset:4672
	v_lshl_add_u64 v[50:51], v[4:5], 0, s[34:35]
	v_lshl_add_u64 v[64:65], v[6:7], 0, s[34:35]
	global_load_dwordx4 v[120:123], v[50:51], off offset:384
	s_waitcnt lgkmcnt(7)
	v_mfma_f32_32x32x16_bf16 a[208:223], v[204:207], v[208:211], a[208:223]
	v_mfma_f32_32x32x16_bf16 a[144:159], v[204:207], v[212:215], a[144:159]
	v_mfma_f32_32x32x16_bf16 a[80:95], v[204:207], v[216:219], a[80:95]
	v_mfma_f32_32x32x16_bf16 a[16:31], v[204:207], v[220:223], a[16:31]
	ds_read_b128 v[204:207], v224 offset:13856
	ds_read_b128 v[196:199], v225 offset:9280
	ds_read_b128 v[200:203], v225 offset:13888
	global_load_dwordx4 v[128:131], v[64:65], off offset:384
	s_waitcnt lgkmcnt(5)
	v_mfma_f32_32x32x16_bf16 a[224:239], v[184:187], v[208:211], a[224:239]
	v_mfma_f32_32x32x16_bf16 a[160:175], v[184:187], v[212:215], a[160:175]
	v_mfma_f32_32x32x16_bf16 a[96:111], v[184:187], v[216:219], a[96:111]
	v_mfma_f32_32x32x16_bf16 a[32:47], v[184:187], v[220:223], a[32:47]
	ds_read_b128 v[184:187], v224 offset:64
	v_lshl_add_u64 v[50:51], v[8:9], 0, s[34:35]
	v_lshl_add_u64 v[64:65], v[10:11], 0, s[34:35]
	global_load_dwordx4 v[132:135], v[50:51], off offset:384
	s_waitcnt lgkmcnt(3)
	v_mfma_f32_32x32x16_bf16 a[240:255], v[204:207], v[208:211], a[240:255]
	v_mfma_f32_32x32x16_bf16 a[176:191], v[204:207], v[212:215], a[176:191]
	v_mfma_f32_32x32x16_bf16 a[112:127], v[204:207], v[216:219], a[112:127]
	v_mfma_f32_32x32x16_bf16 a[48:63], v[204:207], v[220:223], a[48:63]
	ds_read_b128 v[204:207], v224 offset:4672
	global_load_dwordx4 v[136:139], v[64:65], off offset:384
	s_waitcnt vmcnt(16)
; #define GLOAD(RA, RB, kt) { _Pragma("unroll") for (int i = 0; i < 8; ++i) { const int ia = (tail && i >= 4) ? i - 4 : i; \
;     RA[i] = *(const u32x4*)(abase + ((size_t)(32 * ia) * lda + (kt) * 64) * 2 + aoff); RB[i] = *(const u32x4*)(bbase + ((size_t)(32 * i) * K + (kt) * 64) * 2 + boff); } }
; #define LWRITE(RA, RB, buf) { char* as_ = lds + (buf) * 2 * G_TILE; char* bs_ = as_ + G_TILE; _Pragma("unroll") for (int i = 0; i < 8; ++i) { *(u32x4*)(as_ + (lrow + 32 * i) * GS_B + lch * 16) = RA[i]; *(u32x4*)(bs_ + (lrow + 32 * i) * GS_B + lch * 16) = RB[i]; } }
; template <int EPI>
; DEV void gemm_tile(CParams& p, int layer, const bf16_t* __restrict__ A, int lda, const bf16_t* __restrict__ Bt, int K, int m0, int n0, int nt, char* lds, const int swave) {
;     ...
;   GLOAD(ra0, rb0, 0); GLOAD(ra1, rb1, 1); LWRITE(ra0, rb0, 0); __syncthreads();
; #pragma unroll 1
;   for (int kt = 0; kt < nk; kt += 2) {
;     if (kt + 2 < nk) GLOAD(ra0, rb0, kt + 2);
;     COMPUTE(0, ra1, rb1, 1, true);
;     __syncthreads();
;     const bool more = kt + 2 < nk;
;     if (kt + 3 < nk) GLOAD(ra1, rb1, kt + 3);
;     COMPUTE(1, ra0, rb0, 0, more);
	ds_write_b128 v30, v[72:75] offset:9216
	ds_write_b128 v30, v[76:79] offset:46080
	ds_write_b128 v30, v[80:83] offset:13824
	ds_write_b128 v30, v[84:87] offset:50688
	s_waitcnt lgkmcnt(5)
	v_mfma_f32_32x32x16_bf16 a[192:207], v[184:187], v[188:191], a[192:207]
	v_mfma_f32_32x32x16_bf16 a[128:143], v[184:187], v[192:195], a[128:143]
	v_mfma_f32_32x32x16_bf16 a[64:79], v[184:187], v[196:199], a[64:79]
	v_mfma_f32_32x32x16_bf16 a[0:15], v[184:187], v[200:203], a[0:15]
	ds_read_b128 v[184:187], v224 offset:9280
	ds_read_b128 v[208:211], v225 offset:96
	ds_read_b128 v[212:215], v225 offset:4704
	v_lshl_add_u64 v[50:51], v[12:13], 0, s[34:35]
	v_lshl_add_u64 v[64:65], v[14:15], 0, s[34:35]
	global_load_dwordx4 v[140:143], v[50:51], off offset:384
	s_waitcnt lgkmcnt(7)
	v_mfma_f32_32x32x16_bf16 a[208:223], v[204:207], v[188:191], a[208:223]
	v_mfma_f32_32x32x16_bf16 a[144:159], v[204:207], v[192:195], a[144:159]
	v_mfma_f32_32x32x16_bf16 a[80:95], v[204:207], v[196:199], a[80:95]
	v_mfma_f32_32x32x16_bf16 a[16:31], v[204:207], v[200:203], a[16:31]
	ds_read_b128 v[204:207], v224 offset:13888
	ds_read_b128 v[216:219], v225 offset:9312
	ds_read_b128 v[220:223], v225 offset:13920
	global_load_dwordx4 v[148:151], v[64:65], off offset:384
	s_waitcnt lgkmcnt(5)
	v_mfma_f32_32x32x16_bf16 a[224:239], v[184:187], v[188:191], a[224:239]
	v_mfma_f32_32x32x16_bf16 a[160:175], v[184:187], v[192:195], a[160:175]
	v_mfma_f32_32x32x16_bf16 a[96:111], v[184:187], v[196:199], a[96:111]
	v_mfma_f32_32x32x16_bf16 a[32:47], v[184:187], v[200:203], a[32:47]
	ds_read_b128 v[184:187], v224 offset:96
	v_lshl_add_u64 v[50:51], v[16:17], 0, s[34:35]
	v_lshl_add_u64 v[64:65], v[18:19], 0, s[34:35]
	global_load_dwordx4 v[152:155], v[50:51], off offset:384
	s_waitcnt lgkmcnt(3)
	v_mfma_f32_32x32x16_bf16 a[240:255], v[204:207], v[188:191], a[240:255]
	v_mfma_f32_32x32x16_bf16 a[176:191], v[204:207], v[192:195], a[176:191]
	v_mfma_f32_32x32x16_bf16 a[112:127], v[204:207], v[196:199], a[112:127]
	v_mfma_f32_32x32x16_bf16 a[48:63], v[204:207], v[200:203], a[48:63]
	ds_read_b128 v[204:207], v224 offset:4704
	global_load_dwordx4 v[156:159], v[64:65], off offset:384
	s_waitcnt vmcnt(16)
	ds_write_b128 v30, v[88:91] offset:18432
	ds_write_b128 v30, v[92:95] offset:55296
	ds_write_b128 v30, v[96:99] offset:23040
	ds_write_b128 v30, v[108:111] offset:59904
	s_waitcnt lgkmcnt(5)
	v_mfma_f32_32x32x16_bf16 a[192:207], v[184:187], v[208:211], a[192:207]
	v_mfma_f32_32x32x16_bf16 a[128:143], v[184:187], v[212:215], a[128:143]
	v_mfma_f32_32x32x16_bf16 a[64:79], v[184:187], v[216:219], a[64:79]
	v_mfma_f32_32x32x16_bf16 a[0:15], v[184:187], v[220:223], a[0:15]
	ds_read_b128 v[184:187], v224 offset:9312
	v_lshl_add_u64 v[50:51], v[20:21], 0, s[34:35]
	v_lshl_add_u64 v[64:65], v[22:23], 0, s[34:35]
	global_load_dwordx4 v[164:167], v[50:51], off offset:384
	s_waitcnt lgkmcnt(5)
	v_mfma_f32_32x32x16_bf16 a[208:223], v[204:207], v[208:211], a[208:223]
	v_mfma_f32_32x32x16_bf16 a[144:159], v[204:207], v[212:215], a[144:159]
	v_mfma_f32_32x32x16_bf16 a[80:95], v[204:207], v[216:219], a[80:95]
	v_mfma_f32_32x32x16_bf16 a[16:31], v[204:207], v[220:223], a[16:31]
	ds_read_b128 v[204:207], v224 offset:13920
	global_load_dwordx4 v[168:171], v[64:65], off offset:384
	s_waitcnt lgkmcnt(1)
	v_mfma_f32_32x32x16_bf16 a[224:239], v[184:187], v[208:211], a[224:239]
	v_mfma_f32_32x32x16_bf16 a[160:175], v[184:187], v[212:215], a[160:175]
	v_mfma_f32_32x32x16_bf16 a[96:111], v[184:187], v[216:219], a[96:111]
	v_mfma_f32_32x32x16_bf16 a[32:47], v[184:187], v[220:223], a[32:47]
	v_lshl_add_u64 v[50:51], v[24:25], 0, s[34:35]
	v_lshl_add_u64 v[64:65], v[26:27], 0, s[34:35]
	global_load_dwordx4 v[172:175], v[50:51], off offset:384
	s_waitcnt lgkmcnt(0)
	v_mfma_f32_32x32x16_bf16 a[240:255], v[204:207], v[208:211], a[240:255]
	v_mfma_f32_32x32x16_bf16 a[176:191], v[204:207], v[212:215], a[176:191]
	v_mfma_f32_32x32x16_bf16 a[112:127], v[204:207], v[216:219], a[112:127]
	v_mfma_f32_32x32x16_bf16 a[48:63], v[204:207], v[220:223], a[48:63]
	global_load_dwordx4 v[176:179], v[64:65], off offset:384
	s_waitcnt vmcnt(16)
	ds_write_b128 v30, v[124:127] offset:27648
	ds_write_b128 v30, v[144:147] offset:64512
	ds_write_b128 v30, v[160:163] offset:32256
	ds_write_b128 v47, v[180:183]
	s_branch .LBB0_98

; #define GLOAD(RA, RB, kt) { _Pragma("unroll") for (int i = 0; i < 8; ++i) { const int ia = (tail && i >= 4) ? i - 4 : i; \
;     RA[i] = *(const u32x4*)(abase + ((size_t)(32 * ia) * lda + (kt) * 64) * 2 + aoff); RB[i] = *(const u32x4*)(bbase + ((size_t)(32 * i) * K + (kt) * 64) * 2 + boff); } }
; #define LWRITE(RA, RB, buf) { char* as_ = lds + (buf) * 2 * G_TILE; char* bs_ = as_ + G_TILE; _Pragma("unroll") for (int i = 0; i < 8; ++i) { *(u32x4*)(as_ + (lrow + 32 * i) * GS_B + lch * 16) = RA[i]; *(u32x4*)(bs_ + (lrow + 32 * i) * GS_B + lch * 16) = RB[i]; } }
; template <int EPI>
; DEV void gemm_tile(CParams& p, int layer, const bf16_t* __restrict__ A, int lda, const bf16_t* __restrict__ Bt, int K, int m0, int n0, int nt, char* lds, const int swave) {
;     ...
;   const char* asr = lds + (wm * 128 + lr) * GS_B + hh * 16;
;   const char* bsr = lds + G_TILE + (wn * 128 + lr) * GS_B + hh * 16;
;   char* wsw = lds + lrow * GS_B + lch * 16;
;     ...
;   GLOAD(ra0, rb0, 0); GLOAD(ra1, rb1, 1); LWRITE(ra0, rb0, 0); __syncthreads();
; #pragma unroll 1
;   for (int kt = 0; kt < nk; kt += 2) {
;     if (kt + 2 < nk) GLOAD(ra0, rb0, kt + 2);
;     COMPUTE(0, ra1, rb1, 1, true);
;     __syncthreads();
.LBB0_161:
	s_cmp_eq_u32 s86, 0
	s_cbranch_scc0 .Lzi_i2
	ds_read_b128 v[164:167], v26
	ds_read_b128 v[168:171], v26 offset:4608
	ds_read_b128 v[172:175], v26 offset:9216
	ds_read_b128 v[176:179], v26 offset:13824
	ds_read_b128 v[160:163], v25
	ds_read_b128 v[180:183], v25 offset:4608
	s_waitcnt lgkmcnt(1)
	v_mfma_f32_32x32x16_bf16 a[96:111], v[160:163], v[164:167], 0
	v_mfma_f32_32x32x16_bf16 a[0:15], v[160:163], v[168:171], 0
	v_mfma_f32_32x32x16_bf16 a[16:31], v[160:163], v[172:175], 0
	v_mfma_f32_32x32x16_bf16 a[32:47], v[160:163], v[176:179], 0
	ds_read_b128 v[160:163], v25 offset:9216
	ds_read_b128 v[184:187], v26 offset:32
	ds_read_b128 v[188:191], v26 offset:4640
	v_lshl_add_u64 v[28:29], v[2:3], 0, s[34:35]
	v_lshl_add_u64 v[30:31], v[4:5], 0, s[34:35]
	s_add_i32 s2, s100, s28
	s_lshl_b32 s44, s100, 6
	global_load_dwordx4 v[32:35], v[28:29], off
	s_waitcnt lgkmcnt(3)
	v_mfma_f32_32x32x16_bf16 a[80:95], v[180:183], v[164:167], 0
	v_mfma_f32_32x32x16_bf16 a[48:63], v[180:183], v[168:171], 0
	v_mfma_f32_32x32x16_bf16 a[64:79], v[180:183], v[172:175], 0
	v_mfma_f32_32x32x16_bf16 a[112:127], v[180:183], v[176:179], 0
	ds_read_b128 v[180:183], v25 offset:13824
	ds_read_b128 v[192:195], v26 offset:9248
	ds_read_b128 v[196:199], v26 offset:13856
	global_load_dwordx4 v[36:39], v[30:31], off
	s_waitcnt lgkmcnt(5)
	v_mfma_f32_32x32x16_bf16 a[128:143], v[160:163], v[164:167], 0
	v_mfma_f32_32x32x16_bf16 a[144:159], v[160:163], v[168:171], 0
	v_mfma_f32_32x32x16_bf16 a[160:175], v[160:163], v[172:175], 0
	v_mfma_f32_32x32x16_bf16 a[176:191], v[160:163], v[176:179], 0
	ds_read_b128 v[160:163], v25 offset:32
	v_lshl_add_u64 v[28:29], v[28:29], 0, s[8:9]
	v_lshl_add_u64 v[30:31], v[30:31], 0, s[8:9]
	s_lshl_b32 s2, s2, 7
	s_mov_b32 s3, s35
	global_load_dwordx4 v[40:43], v[28:29], off
	s_waitcnt lgkmcnt(3)
	v_mfma_f32_32x32x16_bf16 a[192:207], v[180:183], v[164:167], 0
	v_mfma_f32_32x32x16_bf16 a[208:223], v[180:183], v[168:171], 0
	v_mfma_f32_32x32x16_bf16 a[224:239], v[180:183], v[172:175], 0
	v_mfma_f32_32x32x16_bf16 a[240:255], v[180:183], v[176:179], 0
	ds_read_b128 v[180:183], v25 offset:4640
	global_load_dwordx4 v[44:47], v[30:31], off
	s_waitcnt vmcnt(16)
	ds_write_b128 v8, v[84:87]
	ds_write_b128 v9, v[88:91]
	ds_write_b128 v18, v[96:99]
	ds_write_b128 v19, v[104:107]
	s_waitcnt lgkmcnt(5)
	v_mfma_f32_32x32x16_bf16 a[96:111], v[160:163], v[184:187], a[96:111]
	v_mfma_f32_32x32x16_bf16 a[0:15], v[160:163], v[188:191], a[0:15]
	v_mfma_f32_32x32x16_bf16 a[16:31], v[160:163], v[192:195], a[16:31]
	v_mfma_f32_32x32x16_bf16 a[32:47], v[160:163], v[196:199], a[32:47]
	ds_read_b128 v[160:163], v25 offset:9248
	ds_read_b128 v[164:167], v26 offset:64
	ds_read_b128 v[168:171], v26 offset:4672
	v_lshl_add_u64 v[28:29], v[2:3], 0, s[2:3]
	v_lshl_add_u64 v[30:31], v[4:5], 0, s[2:3]
	s_add_i32 s2, s44, s38
	s_lshl_b32 s2, s2, 1
	global_load_dwordx4 v[48:51], v[28:29], off
	s_waitcnt lgkmcnt(7)
	v_mfma_f32_32x32x16_bf16 a[80:95], v[180:183], v[184:187], a[80:95]
	v_mfma_f32_32x32x16_bf16 a[48:63], v[180:183], v[188:191], a[48:63]
	v_mfma_f32_32x32x16_bf16 a[64:79], v[180:183], v[192:195], a[64:79]
	v_mfma_f32_32x32x16_bf16 a[112:127], v[180:183], v[196:199], a[112:127]
	ds_read_b128 v[180:183], v25 offset:13856
	ds_read_b128 v[172:175], v26 offset:9280
	ds_read_b128 v[176:179], v26 offset:13888
	global_load_dwordx4 v[52:55], v[30:31], off
	s_waitcnt lgkmcnt(5)
	v_mfma_f32_32x32x16_bf16 a[128:143], v[160:163], v[184:187], a[128:143]
	v_mfma_f32_32x32x16_bf16 a[144:159], v[160:163], v[188:191], a[144:159]
	v_mfma_f32_32x32x16_bf16 a[160:175], v[160:163], v[192:195], a[160:175]
	v_mfma_f32_32x32x16_bf16 a[176:191], v[160:163], v[196:199], a[176:191]
	ds_read_b128 v[160:163], v25 offset:64
	v_lshl_add_u64 v[28:29], v[2:3], 0, s[2:3]
	v_lshl_add_u64 v[30:31], v[4:5], 0, s[2:3]
	s_add_i32 s34, s34, s91
	s_add_i32 s2, s44, s39
	global_load_dwordx4 v[56:59], v[28:29], off
	s_waitcnt lgkmcnt(3)
	v_mfma_f32_32x32x16_bf16 a[192:207], v[180:183], v[184:187], a[192:207]
	v_mfma_f32_32x32x16_bf16 a[208:223], v[180:183], v[188:191], a[208:223]
	v_mfma_f32_32x32x16_bf16 a[224:239], v[180:183], v[192:195], a[224:239]
	v_mfma_f32_32x32x16_bf16 a[240:255], v[180:183], v[196:199], a[240:255]
	ds_read_b128 v[180:183], v25 offset:4672
	global_load_dwordx4 v[60:63], v[30:31], off
	s_waitcnt vmcnt(16)
	ds_write_b128 v14, v[112:115]
	ds_write_b128 v15, v[116:119]
	ds_write_b128 v16, v[120:123]
	ds_write_b128 v17, v[124:127]
	s_waitcnt lgkmcnt(5)
	v_mfma_f32_32x32x16_bf16 a[96:111], v[160:163], v[164:167], a[96:111]
	v_mfma_f32_32x32x16_bf16 a[0:15], v[160:163], v[168:171], a[0:15]
	v_mfma_f32_32x32x16_bf16 a[16:31], v[160:163], v[172:175], a[16:31]
	v_mfma_f32_32x32x16_bf16 a[32:47], v[160:163], v[176:179], a[32:47]
	ds_read_b128 v[160:163], v25 offset:9280
	ds_read_b128 v[184:187], v26 offset:96
	ds_read_b128 v[188:191], v26 offset:4704
	v_lshl_add_u64 v[28:29], v[2:3], 0, s[34:35]
	v_lshl_add_u64 v[30:31], v[4:5], 0, s[34:35]
	s_lshl_b32 s34, s2, 1
	s_add_i32 s2, s44, s68
	global_load_dwordx4 v[64:67], v[28:29], off
	s_waitcnt lgkmcnt(7)
	v_mfma_f32_32x32x16_bf16 a[80:95], v[180:183], v[164:167], a[80:95]
	v_mfma_f32_32x32x16_bf16 a[48:63], v[180:183], v[168:171], a[48:63]
	v_mfma_f32_32x32x16_bf16 a[64:79], v[180:183], v[172:175], a[64:79]
	v_mfma_f32_32x32x16_bf16 a[112:127], v[180:183], v[176:179], a[112:127]
	ds_read_b128 v[180:183], v25 offset:13888
	ds_read_b128 v[192:195], v26 offset:9312
	ds_read_b128 v[196:199], v26 offset:13920
	global_load_dwordx4 v[68:71], v[30:31], off
	s_waitcnt lgkmcnt(5)
; #define GLOAD(RA, RB, kt) { _Pragma("unroll") for (int i = 0; i < 8; ++i) { const int ia = (tail && i >= 4) ? i - 4 : i; \
;     RA[i] = *(const u32x4*)(abase + ((size_t)(32 * ia) * lda + (kt) * 64) * 2 + aoff); RB[i] = *(const u32x4*)(bbase + ((size_t)(32 * i) * K + (kt) * 64) * 2 + boff); } }
; #define LWRITE(RA, RB, buf) { char* as_ = lds + (buf) * 2 * G_TILE; char* bs_ = as_ + G_TILE; _Pragma("unroll") for (int i = 0; i < 8; ++i) { *(u32x4*)(as_ + (lrow + 32 * i) * GS_B + lch * 16) = RA[i]; *(u32x4*)(bs_ + (lrow + 32 * i) * GS_B + lch * 16) = RB[i]; } }
; template <int EPI>
; DEV void gemm_tile(CParams& p, int layer, const bf16_t* __restrict__ A, int lda, const bf16_t* __restrict__ Bt, int K, int m0, int n0, int nt, char* lds, const int swave) {
;     ...
;   GLOAD(ra0, rb0, 0); GLOAD(ra1, rb1, 1); LWRITE(ra0, rb0, 0); __syncthreads();
; #pragma unroll 1
;   for (int kt = 0; kt < nk; kt += 2) {
;     if (kt + 2 < nk) GLOAD(ra0, rb0, kt + 2);
;     COMPUTE(0, ra1, rb1, 1, true);
;     __syncthreads();
;     const bool more = kt + 2 < nk;
;     if (kt + 3 < nk) GLOAD(ra1, rb1, kt + 3);
;     COMPUTE(1, ra0, rb0, 0, more);
	v_mfma_f32_32x32x16_bf16 a[128:143], v[160:163], v[164:167], a[128:143]
	v_mfma_f32_32x32x16_bf16 a[144:159], v[160:163], v[168:171], a[144:159]
	v_mfma_f32_32x32x16_bf16 a[160:175], v[160:163], v[172:175], a[160:175]
	v_mfma_f32_32x32x16_bf16 a[176:191], v[160:163], v[176:179], a[176:191]
	ds_read_b128 v[160:163], v25 offset:96
	v_lshl_add_u64 v[28:29], v[2:3], 0, s[34:35]
	v_lshl_add_u64 v[30:31], v[4:5], 0, s[34:35]
	s_lshl_b32 s34, s2, 1
	s_add_i32 s44, s44, s40
	global_load_dwordx4 v[72:75], v[28:29], off
	s_waitcnt lgkmcnt(3)
	v_mfma_f32_32x32x16_bf16 a[192:207], v[180:183], v[164:167], a[192:207]
	v_mfma_f32_32x32x16_bf16 a[208:223], v[180:183], v[168:171], a[208:223]
	v_mfma_f32_32x32x16_bf16 a[224:239], v[180:183], v[172:175], a[224:239]
	v_mfma_f32_32x32x16_bf16 a[240:255], v[180:183], v[176:179], a[240:255]
	ds_read_b128 v[180:183], v25 offset:4704
	global_load_dwordx4 v[76:79], v[30:31], off
	s_waitcnt vmcnt(16)
	ds_write_b128 v10, v[128:131]
	ds_write_b128 v11, v[132:135]
	ds_write_b128 v12, v[136:139]
	ds_write_b128 v13, v[140:143]
	s_waitcnt lgkmcnt(5)
	v_mfma_f32_32x32x16_bf16 a[96:111], v[160:163], v[184:187], a[96:111]
	v_mfma_f32_32x32x16_bf16 a[0:15], v[160:163], v[188:191], a[0:15]
	v_mfma_f32_32x32x16_bf16 a[16:31], v[160:163], v[192:195], a[16:31]
	v_mfma_f32_32x32x16_bf16 a[32:47], v[160:163], v[196:199], a[32:47]
	ds_read_b128 v[160:163], v25 offset:9312
	v_lshl_add_u64 v[28:29], v[2:3], 0, s[34:35]
	v_lshl_add_u64 v[30:31], v[4:5], 0, s[34:35]
	s_lshl_b32 s34, s44, 1
	global_load_dwordx4 v[80:83], v[28:29], off
	s_waitcnt lgkmcnt(5)
	v_mfma_f32_32x32x16_bf16 a[80:95], v[180:183], v[184:187], a[80:95]
	v_mfma_f32_32x32x16_bf16 a[48:63], v[180:183], v[188:191], a[48:63]
	v_mfma_f32_32x32x16_bf16 a[64:79], v[180:183], v[192:195], a[64:79]
	v_mfma_f32_32x32x16_bf16 a[112:127], v[180:183], v[196:199], a[112:127]
	ds_read_b128 v[180:183], v25 offset:13920
	global_load_dwordx4 v[92:95], v[30:31], off
	s_waitcnt lgkmcnt(1)
	v_mfma_f32_32x32x16_bf16 a[128:143], v[160:163], v[184:187], a[128:143]
	v_mfma_f32_32x32x16_bf16 a[144:159], v[160:163], v[188:191], a[144:159]
	v_mfma_f32_32x32x16_bf16 a[160:175], v[160:163], v[192:195], a[160:175]
	v_mfma_f32_32x32x16_bf16 a[176:191], v[160:163], v[196:199], a[176:191]
	v_lshl_add_u64 v[28:29], v[2:3], 0, s[34:35]
	v_lshl_add_u64 v[30:31], v[4:5], 0, s[34:35]
	global_load_dwordx4 v[100:103], v[28:29], off
	s_waitcnt lgkmcnt(0)
	v_mfma_f32_32x32x16_bf16 a[192:207], v[180:183], v[184:187], a[192:207]
	v_mfma_f32_32x32x16_bf16 a[208:223], v[180:183], v[188:191], a[208:223]
	v_mfma_f32_32x32x16_bf16 a[224:239], v[180:183], v[192:195], a[224:239]
	v_mfma_f32_32x32x16_bf16 a[240:255], v[180:183], v[196:199], a[240:255]
	global_load_dwordx4 v[108:111], v[30:31], off
	s_waitcnt vmcnt(16)
	ds_write_b128 v20, v[144:147]
	ds_write_b128 v21, v[148:151]
	ds_write_b128 v22, v[152:155]
	ds_write_b128 v23, v[156:159]
	s_branch .LBB0_177
.Lzi_i2:
	ds_read_b128 v[164:167], v26
	ds_read_b128 v[168:171], v26 offset:4608
	ds_read_b128 v[172:175], v26 offset:9216
	ds_read_b128 v[176:179], v26 offset:13824
	ds_read_b128 v[160:163], v25
	ds_read_b128 v[180:183], v25 offset:4608
	s_waitcnt lgkmcnt(1)
	v_mfma_f32_32x32x16_bf16 a[96:111], v[160:163], v[164:167], a[96:111]
	v_mfma_f32_32x32x16_bf16 a[0:15], v[160:163], v[168:171], a[0:15]
	v_mfma_f32_32x32x16_bf16 a[16:31], v[160:163], v[172:175], a[16:31]
	v_mfma_f32_32x32x16_bf16 a[32:47], v[160:163], v[176:179], a[32:47]
	ds_read_b128 v[160:163], v25 offset:9216
	ds_read_b128 v[184:187], v26 offset:32
	ds_read_b128 v[188:191], v26 offset:4640
	v_lshl_add_u64 v[28:29], v[2:3], 0, s[34:35]
	v_lshl_add_u64 v[30:31], v[4:5], 0, s[34:35]
	s_add_i32 s2, s100, s28
	s_lshl_b32 s44, s100, 6
	global_load_dwordx4 v[32:35], v[28:29], off
	s_waitcnt lgkmcnt(3)
	v_mfma_f32_32x32x16_bf16 a[80:95], v[180:183], v[164:167], a[80:95]
	v_mfma_f32_32x32x16_bf16 a[48:63], v[180:183], v[168:171], a[48:63]
	v_mfma_f32_32x32x16_bf16 a[64:79], v[180:183], v[172:175], a[64:79]
	v_mfma_f32_32x32x16_bf16 a[112:127], v[180:183], v[176:179], a[112:127]
	ds_read_b128 v[180:183], v25 offset:13824
	ds_read_b128 v[192:195], v26 offset:9248
	ds_read_b128 v[196:199], v26 offset:13856
	global_load_dwordx4 v[36:39], v[30:31], off
	s_waitcnt lgkmcnt(5)
	v_mfma_f32_32x32x16_bf16 a[128:143], v[160:163], v[164:167], a[128:143]
	v_mfma_f32_32x32x16_bf16 a[144:159], v[160:163], v[168:171], a[144:159]
	v_mfma_f32_32x32x16_bf16 a[160:175], v[160:163], v[172:175], a[160:175]
	v_mfma_f32_32x32x16_bf16 a[176:191], v[160:163], v[176:179], a[176:191]
	ds_read_b128 v[160:163], v25 offset:32
	v_lshl_add_u64 v[28:29], v[28:29], 0, s[8:9]
	v_lshl_add_u64 v[30:31], v[30:31], 0, s[8:9]
	s_lshl_b32 s2, s2, 7
	s_mov_b32 s3, s35
	global_load_dwordx4 v[40:43], v[28:29], off
	s_waitcnt lgkmcnt(3)
	v_mfma_f32_32x32x16_bf16 a[192:207], v[180:183], v[164:167], a[192:207]
	v_mfma_f32_32x32x16_bf16 a[208:223], v[180:183], v[168:171], a[208:223]
	v_mfma_f32_32x32x16_bf16 a[224:239], v[180:183], v[172:175], a[224:239]
	v_mfma_f32_32x32x16_bf16 a[240:255], v[180:183], v[176:179], a[240:255]
	ds_read_b128 v[180:183], v25 offset:4640
	global_load_dwordx4 v[44:47], v[30:31], off
	s_waitcnt vmcnt(16)
	ds_write_b128 v8, v[84:87]
	ds_write_b128 v9, v[88:91]
	ds_write_b128 v18, v[96:99]
	ds_write_b128 v19, v[104:107]
	s_waitcnt lgkmcnt(5)
; #define GLOAD(RA, RB, kt) { _Pragma("unroll") for (int i = 0; i < 8; ++i) { const int ia = (tail && i >= 4) ? i - 4 : i; \
;     RA[i] = *(const u32x4*)(abase + ((size_t)(32 * ia) * lda + (kt) * 64) * 2 + aoff); RB[i] = *(const u32x4*)(bbase + ((size_t)(32 * i) * K + (kt) * 64) * 2 + boff); } }
; #define LWRITE(RA, RB, buf) { char* as_ = lds + (buf) * 2 * G_TILE; char* bs_ = as_ + G_TILE; _Pragma("unroll") for (int i = 0; i < 8; ++i) { *(u32x4*)(as_ + (lrow + 32 * i) * GS_B + lch * 16) = RA[i]; *(u32x4*)(bs_ + (lrow + 32 * i) * GS_B + lch * 16) = RB[i]; } }
; template <int EPI>
; DEV void gemm_tile(CParams& p, int layer, const bf16_t* __restrict__ A, int lda, const bf16_t* __restrict__ Bt, int K, int m0, int n0, int nt, char* lds, const int swave) {
;     ...
;   GLOAD(ra0, rb0, 0); GLOAD(ra1, rb1, 1); LWRITE(ra0, rb0, 0); __syncthreads();
; #pragma unroll 1
;   for (int kt = 0; kt < nk; kt += 2) {
;     if (kt + 2 < nk) GLOAD(ra0, rb0, kt + 2);
;     COMPUTE(0, ra1, rb1, 1, true);
;     __syncthreads();
;     const bool more = kt + 2 < nk;
;     if (kt + 3 < nk) GLOAD(ra1, rb1, kt + 3);
;     COMPUTE(1, ra0, rb0, 0, more);
	v_mfma_f32_32x32x16_bf16 a[96:111], v[160:163], v[184:187], a[96:111]
	v_mfma_f32_32x32x16_bf16 a[0:15], v[160:163], v[188:191], a[0:15]
	v_mfma_f32_32x32x16_bf16 a[16:31], v[160:163], v[192:195], a[16:31]
	v_mfma_f32_32x32x16_bf16 a[32:47], v[160:163], v[196:199], a[32:47]
	ds_read_b128 v[160:163], v25 offset:9248
	ds_read_b128 v[164:167], v26 offset:64
	ds_read_b128 v[168:171], v26 offset:4672
	v_lshl_add_u64 v[28:29], v[2:3], 0, s[2:3]
	v_lshl_add_u64 v[30:31], v[4:5], 0, s[2:3]
	s_add_i32 s2, s44, s38
	s_lshl_b32 s2, s2, 1
	global_load_dwordx4 v[48:51], v[28:29], off
	s_waitcnt lgkmcnt(7)
	v_mfma_f32_32x32x16_bf16 a[80:95], v[180:183], v[184:187], a[80:95]
	v_mfma_f32_32x32x16_bf16 a[48:63], v[180:183], v[188:191], a[48:63]
	v_mfma_f32_32x32x16_bf16 a[64:79], v[180:183], v[192:195], a[64:79]
	v_mfma_f32_32x32x16_bf16 a[112:127], v[180:183], v[196:199], a[112:127]
	ds_read_b128 v[180:183], v25 offset:13856
	ds_read_b128 v[172:175], v26 offset:9280
	ds_read_b128 v[176:179], v26 offset:13888
	global_load_dwordx4 v[52:55], v[30:31], off
	s_waitcnt lgkmcnt(5)
	v_mfma_f32_32x32x16_bf16 a[128:143], v[160:163], v[184:187], a[128:143]
	v_mfma_f32_32x32x16_bf16 a[144:159], v[160:163], v[188:191], a[144:159]
	v_mfma_f32_32x32x16_bf16 a[160:175], v[160:163], v[192:195], a[160:175]
	v_mfma_f32_32x32x16_bf16 a[176:191], v[160:163], v[196:199], a[176:191]
	ds_read_b128 v[160:163], v25 offset:64
	v_lshl_add_u64 v[28:29], v[2:3], 0, s[2:3]
	v_lshl_add_u64 v[30:31], v[4:5], 0, s[2:3]
	s_add_i32 s34, s34, s91
	s_add_i32 s2, s44, s39
	global_load_dwordx4 v[56:59], v[28:29], off
	s_waitcnt lgkmcnt(3)
	v_mfma_f32_32x32x16_bf16 a[192:207], v[180:183], v[184:187], a[192:207]
	v_mfma_f32_32x32x16_bf16 a[208:223], v[180:183], v[188:191], a[208:223]
	v_mfma_f32_32x32x16_bf16 a[224:239], v[180:183], v[192:195], a[224:239]
	v_mfma_f32_32x32x16_bf16 a[240:255], v[180:183], v[196:199], a[240:255]
	ds_read_b128 v[180:183], v25 offset:4672
	global_load_dwordx4 v[60:63], v[30:31], off
	s_waitcnt vmcnt(16)
	ds_write_b128 v14, v[112:115]
	ds_write_b128 v15, v[116:119]
	ds_write_b128 v16, v[120:123]
	ds_write_b128 v17, v[124:127]
	s_waitcnt lgkmcnt(5)
	v_mfma_f32_32x32x16_bf16 a[96:111], v[160:163], v[164:167], a[96:111]
	v_mfma_f32_32x32x16_bf16 a[0:15], v[160:163], v[168:171], a[0:15]
	v_mfma_f32_32x32x16_bf16 a[16:31], v[160:163], v[172:175], a[16:31]
	v_mfma_f32_32x32x16_bf16 a[32:47], v[160:163], v[176:179], a[32:47]
	ds_read_b128 v[160:163], v25 offset:9280
	ds_read_b128 v[184:187], v26 offset:96
	ds_read_b128 v[188:191], v26 offset:4704
	v_lshl_add_u64 v[28:29], v[2:3], 0, s[34:35]
	v_lshl_add_u64 v[30:31], v[4:5], 0, s[34:35]
	s_lshl_b32 s34, s2, 1
	s_add_i32 s2, s44, s68
	global_load_dwordx4 v[64:67], v[28:29], off
	s_waitcnt lgkmcnt(7)
	v_mfma_f32_32x32x16_bf16 a[80:95], v[180:183], v[164:167], a[80:95]
	v_mfma_f32_32x32x16_bf16 a[48:63], v[180:183], v[168:171], a[48:63]
	v_mfma_f32_32x32x16_bf16 a[64:79], v[180:183], v[172:175], a[64:79]
	v_mfma_f32_32x32x16_bf16 a[112:127], v[180:183], v[176:179], a[112:127]
	ds_read_b128 v[180:183], v25 offset:13888
	ds_read_b128 v[192:195], v26 offset:9312
	ds_read_b128 v[196:199], v26 offset:13920
	global_load_dwordx4 v[68:71], v[30:31], off
	s_waitcnt lgkmcnt(5)
	v_mfma_f32_32x32x16_bf16 a[128:143], v[160:163], v[164:167], a[128:143]
	v_mfma_f32_32x32x16_bf16 a[144:159], v[160:163], v[168:171], a[144:159]
	v_mfma_f32_32x32x16_bf16 a[160:175], v[160:163], v[172:175], a[160:175]
	v_mfma_f32_32x32x16_bf16 a[176:191], v[160:163], v[176:179], a[176:191]
	ds_read_b128 v[160:163], v25 offset:96
	v_lshl_add_u64 v[28:29], v[2:3], 0, s[34:35]
	v_lshl_add_u64 v[30:31], v[4:5], 0, s[34:35]
	s_lshl_b32 s34, s2, 1
	s_add_i32 s44, s44, s40
	global_load_dwordx4 v[72:75], v[28:29], off
	s_waitcnt lgkmcnt(3)
	v_mfma_f32_32x32x16_bf16 a[192:207], v[180:183], v[164:167], a[192:207]
	v_mfma_f32_32x32x16_bf16 a[208:223], v[180:183], v[168:171], a[208:223]
	v_mfma_f32_32x32x16_bf16 a[224:239], v[180:183], v[172:175], a[224:239]
	v_mfma_f32_32x32x16_bf16 a[240:255], v[180:183], v[176:179], a[240:255]
	ds_read_b128 v[180:183], v25 offset:4704
	global_load_dwordx4 v[76:79], v[30:31], off
	s_waitcnt vmcnt(16)
	ds_write_b128 v10, v[128:131]
	ds_write_b128 v11, v[132:135]
	ds_write_b128 v12, v[136:139]
	ds_write_b128 v13, v[140:143]
	s_waitcnt lgkmcnt(5)
	v_mfma_f32_32x32x16_bf16 a[96:111], v[160:163], v[184:187], a[96:111]
	v_mfma_f32_32x32x16_bf16 a[0:15], v[160:163], v[188:191], a[0:15]
	v_mfma_f32_32x32x16_bf16 a[16:31], v[160:163], v[192:195], a[16:31]
	v_mfma_f32_32x32x16_bf16 a[32:47], v[160:163], v[196:199], a[32:47]
	ds_read_b128 v[160:163], v25 offset:9312
	v_lshl_add_u64 v[28:29], v[2:3], 0, s[34:35]
	v_lshl_add_u64 v[30:31], v[4:5], 0, s[34:35]
	s_lshl_b32 s34, s44, 1
	global_load_dwordx4 v[80:83], v[28:29], off
	s_waitcnt lgkmcnt(5)
	v_mfma_f32_32x32x16_bf16 a[80:95], v[180:183], v[184:187], a[80:95]
	v_mfma_f32_32x32x16_bf16 a[48:63], v[180:183], v[188:191], a[48:63]
	v_mfma_f32_32x32x16_bf16 a[64:79], v[180:183], v[192:195], a[64:79]
	v_mfma_f32_32x32x16_bf16 a[112:127], v[180:183], v[196:199], a[112:127]
	ds_read_b128 v[180:183], v25 offset:13920
	global_load_dwordx4 v[92:95], v[30:31], off
	s_waitcnt lgkmcnt(1)
	v_mfma_f32_32x32x16_bf16 a[128:143], v[160:163], v[184:187], a[128:143]
	v_mfma_f32_32x32x16_bf16 a[144:159], v[160:163], v[188:191], a[144:159]
	v_mfma_f32_32x32x16_bf16 a[160:175], v[160:163], v[192:195], a[160:175]
	v_mfma_f32_32x32x16_bf16 a[176:191], v[160:163], v[196:199], a[176:191]
	v_lshl_add_u64 v[28:29], v[2:3], 0, s[34:35]
	v_lshl_add_u64 v[30:31], v[4:5], 0, s[34:35]
	global_load_dwordx4 v[100:103], v[28:29], off
	s_waitcnt lgkmcnt(0)
	v_mfma_f32_32x32x16_bf16 a[192:207], v[180:183], v[184:187], a[192:207]
	v_mfma_f32_32x32x16_bf16 a[208:223], v[180:183], v[188:191], a[208:223]
	v_mfma_f32_32x32x16_bf16 a[224:239], v[180:183], v[192:195], a[224:239]
	v_mfma_f32_32x32x16_bf16 a[240:255], v[180:183], v[196:199], a[240:255]
	global_load_dwordx4 v[108:111], v[30:31], off
	s_waitcnt vmcnt(16)
	ds_write_b128 v20, v[144:147]
	ds_write_b128 v21, v[148:151]
	ds_write_b128 v22, v[152:155]
	ds_write_b128 v23, v[156:159]

; #define GLOAD(RA, RB, kt) { _Pragma("unroll") for (int i = 0; i < 8; ++i) { const int ia = (tail && i >= 4) ? i - 4 : i; \
;     RA[i] = *(const u32x4*)(abase + ((size_t)(32 * ia) * lda + (kt) * 64) * 2 + aoff); RB[i] = *(const u32x4*)(bbase + ((size_t)(32 * i) * K + (kt) * 64) * 2 + boff); } }
; #define LWRITE(RA, RB, buf) { char* as_ = lds + (buf) * 2 * G_TILE; char* bs_ = as_ + G_TILE; _Pragma("unroll") for (int i = 0; i < 8; ++i) { *(u32x4*)(as_ + (lrow + 32 * i) * GS_B + lch * 16) = RA[i]; *(u32x4*)(bs_ + (lrow + 32 * i) * GS_B + lch * 16) = RB[i]; } }
; template <int EPI>
; DEV void gemm_tile(CParams& p, int layer, const bf16_t* __restrict__ A, int lda, const bf16_t* __restrict__ Bt, int K, int m0, int n0, int nt, char* lds, const int swave) {
;     ...
;   GLOAD(ra0, rb0, 0); GLOAD(ra1, rb1, 1); LWRITE(ra0, rb0, 0); __syncthreads();
; #pragma unroll 1
;   for (int kt = 0; kt < nk; kt += 2) {
;     if (kt + 2 < nk) GLOAD(ra0, rb0, kt + 2);
;     COMPUTE(0, ra1, rb1, 1, true);
;     __syncthreads();
;     const bool more = kt + 2 < nk;
;     if (kt + 3 < nk) GLOAD(ra1, rb1, kt + 3);
;     COMPUTE(1, ra0, rb0, 0, more);
.LBB0_179:
	v_add_u32_e32 v200, 0x1b000, v6
	v_add_u32_e32 v201, 0x12000, v26
	s_andn2_b64 vcc, exec, s[60:61]
	s_cbranch_vccnz .Lpg_i2_nomore
	ds_read_b128 v[164:167], v201
	ds_read_b128 v[168:171], v201 offset:4608
	ds_read_b128 v[172:175], v201 offset:9216
	ds_read_b128 v[176:179], v201 offset:13824
	ds_read_b128 v[160:163], v200
	ds_read_b128 v[180:183], v200 offset:4608
	s_waitcnt lgkmcnt(1)
	v_mfma_f32_32x32x16_bf16 a[96:111], v[160:163], v[164:167], a[96:111]
	v_mfma_f32_32x32x16_bf16 a[0:15], v[160:163], v[168:171], a[0:15]
	v_mfma_f32_32x32x16_bf16 a[16:31], v[160:163], v[172:175], a[16:31]
	v_mfma_f32_32x32x16_bf16 a[32:47], v[160:163], v[176:179], a[32:47]
	ds_read_b128 v[160:163], v200 offset:9216
	ds_read_b128 v[184:187], v201 offset:32
	ds_read_b128 v[188:191], v201 offset:4640
	s_lshl_b32 s34, s2, 7
	s_lshl_b32 s44, s2, 6
	v_lshl_add_u64 v[28:29], v[2:3], 0, s[34:35]
	v_lshl_add_u64 v[30:31], v[4:5], 0, s[34:35]
	s_add_i32 s2, s2, s28
	global_load_dwordx4 v[84:87], v[28:29], off
	s_waitcnt lgkmcnt(3)
	v_mfma_f32_32x32x16_bf16 a[80:95], v[180:183], v[164:167], a[80:95]
	v_mfma_f32_32x32x16_bf16 a[48:63], v[180:183], v[168:171], a[48:63]
	v_mfma_f32_32x32x16_bf16 a[64:79], v[180:183], v[172:175], a[64:79]
	v_mfma_f32_32x32x16_bf16 a[112:127], v[180:183], v[176:179], a[112:127]
	ds_read_b128 v[180:183], v200 offset:13824
	ds_read_b128 v[192:195], v201 offset:9248
	ds_read_b128 v[196:199], v201 offset:13856
	global_load_dwordx4 v[88:91], v[30:31], off
	s_waitcnt lgkmcnt(5)
	v_mfma_f32_32x32x16_bf16 a[128:143], v[160:163], v[164:167], a[128:143]
	v_mfma_f32_32x32x16_bf16 a[144:159], v[160:163], v[168:171], a[144:159]
	v_mfma_f32_32x32x16_bf16 a[160:175], v[160:163], v[172:175], a[160:175]
	v_mfma_f32_32x32x16_bf16 a[176:191], v[160:163], v[176:179], a[176:191]
	ds_read_b128 v[160:163], v200 offset:32
	v_lshl_add_u64 v[28:29], v[28:29], 0, s[8:9]
	v_lshl_add_u64 v[30:31], v[30:31], 0, s[8:9]
	s_lshl_b32 s2, s2, 7
	s_mov_b32 s3, s35
	global_load_dwordx4 v[96:99], v[28:29], off
	s_waitcnt lgkmcnt(3)
	v_mfma_f32_32x32x16_bf16 a[192:207], v[180:183], v[164:167], a[192:207]
	v_mfma_f32_32x32x16_bf16 a[208:223], v[180:183], v[168:171], a[208:223]
	v_mfma_f32_32x32x16_bf16 a[224:239], v[180:183], v[172:175], a[224:239]
	v_mfma_f32_32x32x16_bf16 a[240:255], v[180:183], v[176:179], a[240:255]
	ds_read_b128 v[180:183], v200 offset:4640
	global_load_dwordx4 v[104:107], v[30:31], off
	s_waitcnt vmcnt(16)
	ds_write_b128 v7, v[32:35]
	ds_write_b128 v7, v[36:39] offset:36864
	ds_write_b128 v7, v[40:43] offset:4608
	ds_write_b128 v7, v[44:47] offset:41472
	s_waitcnt lgkmcnt(5)
	v_mfma_f32_32x32x16_bf16 a[96:111], v[160:163], v[184:187], a[96:111]
	v_mfma_f32_32x32x16_bf16 a[0:15], v[160:163], v[188:191], a[0:15]
	v_mfma_f32_32x32x16_bf16 a[16:31], v[160:163], v[192:195], a[16:31]
	v_mfma_f32_32x32x16_bf16 a[32:47], v[160:163], v[196:199], a[32:47]
	ds_read_b128 v[160:163], v200 offset:9248
	ds_read_b128 v[164:167], v201 offset:64
	ds_read_b128 v[168:171], v201 offset:4672
	v_lshl_add_u64 v[28:29], v[2:3], 0, s[2:3]
	v_lshl_add_u64 v[30:31], v[4:5], 0, s[2:3]
	s_add_i32 s2, s44, s38
	s_lshl_b32 s2, s2, 1
	global_load_dwordx4 v[112:115], v[28:29], off
	s_waitcnt lgkmcnt(7)
	v_mfma_f32_32x32x16_bf16 a[80:95], v[180:183], v[184:187], a[80:95]
	v_mfma_f32_32x32x16_bf16 a[48:63], v[180:183], v[188:191], a[48:63]
	v_mfma_f32_32x32x16_bf16 a[64:79], v[180:183], v[192:195], a[64:79]
	v_mfma_f32_32x32x16_bf16 a[112:127], v[180:183], v[196:199], a[112:127]
	ds_read_b128 v[180:183], v200 offset:13856
	ds_read_b128 v[172:175], v201 offset:9280
	ds_read_b128 v[176:179], v201 offset:13888
	global_load_dwordx4 v[116:119], v[30:31], off
	s_waitcnt lgkmcnt(5)
	v_mfma_f32_32x32x16_bf16 a[128:143], v[160:163], v[184:187], a[128:143]
	v_mfma_f32_32x32x16_bf16 a[144:159], v[160:163], v[188:191], a[144:159]
	v_mfma_f32_32x32x16_bf16 a[160:175], v[160:163], v[192:195], a[160:175]
	v_mfma_f32_32x32x16_bf16 a[176:191], v[160:163], v[196:199], a[176:191]
	ds_read_b128 v[160:163], v200 offset:64
	v_lshl_add_u64 v[28:29], v[2:3], 0, s[2:3]
	v_lshl_add_u64 v[30:31], v[4:5], 0, s[2:3]
	s_add_i32 s34, s34, s91
	s_add_i32 s2, s44, s39
	global_load_dwordx4 v[120:123], v[28:29], off
	s_waitcnt lgkmcnt(3)
	v_mfma_f32_32x32x16_bf16 a[192:207], v[180:183], v[184:187], a[192:207]
	v_mfma_f32_32x32x16_bf16 a[208:223], v[180:183], v[188:191], a[208:223]
	v_mfma_f32_32x32x16_bf16 a[224:239], v[180:183], v[192:195], a[224:239]
	v_mfma_f32_32x32x16_bf16 a[240:255], v[180:183], v[196:199], a[240:255]
	ds_read_b128 v[180:183], v200 offset:4672
	global_load_dwordx4 v[124:127], v[30:31], off
	s_waitcnt vmcnt(16)
; #define GLOAD(RA, RB, kt) { _Pragma("unroll") for (int i = 0; i < 8; ++i) { const int ia = (tail && i >= 4) ? i - 4 : i; \
;     RA[i] = *(const u32x4*)(abase + ((size_t)(32 * ia) * lda + (kt) * 64) * 2 + aoff); RB[i] = *(const u32x4*)(bbase + ((size_t)(32 * i) * K + (kt) * 64) * 2 + boff); } }
; #define LWRITE(RA, RB, buf) { char* as_ = lds + (buf) * 2 * G_TILE; char* bs_ = as_ + G_TILE; _Pragma("unroll") for (int i = 0; i < 8; ++i) { *(u32x4*)(as_ + (lrow + 32 * i) * GS_B + lch * 16) = RA[i]; *(u32x4*)(bs_ + (lrow + 32 * i) * GS_B + lch * 16) = RB[i]; } }
; template <int EPI>
; DEV void gemm_tile(CParams& p, int layer, const bf16_t* __restrict__ A, int lda, const bf16_t* __restrict__ Bt, int K, int m0, int n0, int nt, char* lds, const int swave) {
;     ...
;   GLOAD(ra0, rb0, 0); GLOAD(ra1, rb1, 1); LWRITE(ra0, rb0, 0); __syncthreads();
; #pragma unroll 1
;   for (int kt = 0; kt < nk; kt += 2) {
;     if (kt + 2 < nk) GLOAD(ra0, rb0, kt + 2);
;     COMPUTE(0, ra1, rb1, 1, true);
;     __syncthreads();
;     const bool more = kt + 2 < nk;
;     if (kt + 3 < nk) GLOAD(ra1, rb1, kt + 3);
;     COMPUTE(1, ra0, rb0, 0, more);
	ds_write_b128 v7, v[48:51] offset:9216
	ds_write_b128 v7, v[52:55] offset:46080
	ds_write_b128 v7, v[56:59] offset:13824
	ds_write_b128 v7, v[60:63] offset:50688
	s_waitcnt lgkmcnt(5)
	v_mfma_f32_32x32x16_bf16 a[96:111], v[160:163], v[164:167], a[96:111]
	v_mfma_f32_32x32x16_bf16 a[0:15], v[160:163], v[168:171], a[0:15]
	v_mfma_f32_32x32x16_bf16 a[16:31], v[160:163], v[172:175], a[16:31]
	v_mfma_f32_32x32x16_bf16 a[32:47], v[160:163], v[176:179], a[32:47]
	ds_read_b128 v[160:163], v200 offset:9280
	ds_read_b128 v[184:187], v201 offset:96
	ds_read_b128 v[188:191], v201 offset:4704
	v_lshl_add_u64 v[28:29], v[2:3], 0, s[34:35]
	v_lshl_add_u64 v[30:31], v[4:5], 0, s[34:35]
	s_lshl_b32 s34, s2, 1
	s_add_i32 s2, s44, s68
	global_load_dwordx4 v[128:131], v[28:29], off
	s_waitcnt lgkmcnt(7)
	v_mfma_f32_32x32x16_bf16 a[80:95], v[180:183], v[164:167], a[80:95]
	v_mfma_f32_32x32x16_bf16 a[48:63], v[180:183], v[168:171], a[48:63]
	v_mfma_f32_32x32x16_bf16 a[64:79], v[180:183], v[172:175], a[64:79]
	v_mfma_f32_32x32x16_bf16 a[112:127], v[180:183], v[176:179], a[112:127]
	ds_read_b128 v[180:183], v200 offset:13888
	ds_read_b128 v[192:195], v201 offset:9312
	ds_read_b128 v[196:199], v201 offset:13920
	global_load_dwordx4 v[132:135], v[30:31], off
	s_waitcnt lgkmcnt(5)
	v_mfma_f32_32x32x16_bf16 a[128:143], v[160:163], v[164:167], a[128:143]
	v_mfma_f32_32x32x16_bf16 a[144:159], v[160:163], v[168:171], a[144:159]
	v_mfma_f32_32x32x16_bf16 a[160:175], v[160:163], v[172:175], a[160:175]
	v_mfma_f32_32x32x16_bf16 a[176:191], v[160:163], v[176:179], a[176:191]
	ds_read_b128 v[160:163], v200 offset:96
	v_lshl_add_u64 v[28:29], v[2:3], 0, s[34:35]
	v_lshl_add_u64 v[30:31], v[4:5], 0, s[34:35]
	s_lshl_b32 s34, s2, 1
	s_add_i32 s44, s44, s40
	global_load_dwordx4 v[136:139], v[28:29], off
	s_waitcnt lgkmcnt(3)
	v_mfma_f32_32x32x16_bf16 a[192:207], v[180:183], v[164:167], a[192:207]
	v_mfma_f32_32x32x16_bf16 a[208:223], v[180:183], v[168:171], a[208:223]
	v_mfma_f32_32x32x16_bf16 a[224:239], v[180:183], v[172:175], a[224:239]
	v_mfma_f32_32x32x16_bf16 a[240:255], v[180:183], v[176:179], a[240:255]
	ds_read_b128 v[180:183], v200 offset:4704
	global_load_dwordx4 v[140:143], v[30:31], off
	s_waitcnt vmcnt(16)
	ds_write_b128 v7, v[64:67] offset:18432
	ds_write_b128 v7, v[68:71] offset:55296
	ds_write_b128 v7, v[72:75] offset:23040
	ds_write_b128 v7, v[76:79] offset:59904
	s_waitcnt lgkmcnt(5)
	v_mfma_f32_32x32x16_bf16 a[96:111], v[160:163], v[184:187], a[96:111]
	v_mfma_f32_32x32x16_bf16 a[0:15], v[160:163], v[188:191], a[0:15]
	v_mfma_f32_32x32x16_bf16 a[16:31], v[160:163], v[192:195], a[16:31]
	v_mfma_f32_32x32x16_bf16 a[32:47], v[160:163], v[196:199], a[32:47]
	ds_read_b128 v[160:163], v200 offset:9312
	v_lshl_add_u64 v[28:29], v[2:3], 0, s[34:35]
	v_lshl_add_u64 v[30:31], v[4:5], 0, s[34:35]
	s_lshl_b32 s34, s44, 1
	global_load_dwordx4 v[144:147], v[28:29], off
	s_waitcnt lgkmcnt(5)
	v_mfma_f32_32x32x16_bf16 a[80:95], v[180:183], v[184:187], a[80:95]
	v_mfma_f32_32x32x16_bf16 a[48:63], v[180:183], v[188:191], a[48:63]
	v_mfma_f32_32x32x16_bf16 a[64:79], v[180:183], v[192:195], a[64:79]
	v_mfma_f32_32x32x16_bf16 a[112:127], v[180:183], v[196:199], a[112:127]
	ds_read_b128 v[180:183], v200 offset:13920
	global_load_dwordx4 v[148:151], v[30:31], off
	s_waitcnt lgkmcnt(1)
	v_mfma_f32_32x32x16_bf16 a[128:143], v[160:163], v[184:187], a[128:143]
	v_mfma_f32_32x32x16_bf16 a[144:159], v[160:163], v[188:191], a[144:159]
	v_mfma_f32_32x32x16_bf16 a[160:175], v[160:163], v[192:195], a[160:175]
	v_mfma_f32_32x32x16_bf16 a[176:191], v[160:163], v[196:199], a[176:191]
	v_lshl_add_u64 v[28:29], v[2:3], 0, s[34:35]
	v_lshl_add_u64 v[30:31], v[4:5], 0, s[34:35]
	global_load_dwordx4 v[152:155], v[28:29], off
	s_waitcnt lgkmcnt(0)
	v_mfma_f32_32x32x16_bf16 a[192:207], v[180:183], v[184:187], a[192:207]
	v_mfma_f32_32x32x16_bf16 a[208:223], v[180:183], v[188:191], a[208:223]
	v_mfma_f32_32x32x16_bf16 a[224:239], v[180:183], v[192:195], a[224:239]
	v_mfma_f32_32x32x16_bf16 a[240:255], v[180:183], v[196:199], a[240:255]
	global_load_dwordx4 v[156:159], v[30:31], off
	s_waitcnt vmcnt(16)
	ds_write_b128 v7, v[80:83] offset:27648
	ds_write_b128 v7, v[92:95] offset:64512
	ds_write_b128 v7, v[100:103] offset:32256
	ds_write_b128 v24, v[108:111]
	s_branch .LBB0_158

; #define GLOAD(RA, RB, kt) { _Pragma("unroll") for (int i = 0; i < 8; ++i) { const int ia = (tail && i >= 4) ? i - 4 : i; \
;     RA[i] = *(const u32x4*)(abase + ((size_t)(32 * ia) * lda + (kt) * 64) * 2 + aoff); RB[i] = *(const u32x4*)(bbase + ((size_t)(32 * i) * K + (kt) * 64) * 2 + boff); } }
; #define LWRITE(RA, RB, buf) { char* as_ = lds + (buf) * 2 * G_TILE; char* bs_ = as_ + G_TILE; _Pragma("unroll") for (int i = 0; i < 8; ++i) { *(u32x4*)(as_ + (lrow + 32 * i) * GS_B + lch * 16) = RA[i]; *(u32x4*)(bs_ + (lrow + 32 * i) * GS_B + lch * 16) = RB[i]; } }
; template <int EPI>
; DEV void gemm_tile(CParams& p, int layer, const bf16_t* __restrict__ A, int lda, const bf16_t* __restrict__ Bt, int K, int m0, int n0, int nt, char* lds, const int swave) {
;     ...
;   const char* asr = lds + (wm * 128 + lr) * GS_B + hh * 16;
;   const char* bsr = lds + G_TILE + (wn * 128 + lr) * GS_B + hh * 16;
;   char* wsw = lds + lrow * GS_B + lch * 16;
;     ...
;   GLOAD(ra0, rb0, 0); GLOAD(ra1, rb1, 1); LWRITE(ra0, rb0, 0); __syncthreads();
; #pragma unroll 1
;   for (int kt = 0; kt < nk; kt += 2) {
;     if (kt + 2 < nk) GLOAD(ra0, rb0, kt + 2);
;     COMPUTE(0, ra1, rb1, 1, true);
;     __syncthreads();
.LBB0_921:
	s_cmp_eq_u32 s42, 0
	s_cbranch_scc0 .Lzi_i3
	ds_read_b128 v[184:187], v45
	ds_read_b128 v[188:191], v45 offset:4608
	ds_read_b128 v[192:195], v45 offset:9216
	ds_read_b128 v[196:199], v45 offset:13824
	ds_read_b128 v[180:183], v49
	ds_read_b128 v[204:207], v49 offset:4608
	s_waitcnt lgkmcnt(1)
	v_mfma_f32_32x32x16_bf16 a[0:15], v[180:183], v[184:187], 0
	v_mfma_f32_32x32x16_bf16 a[16:31], v[180:183], v[188:191], 0
	v_mfma_f32_32x32x16_bf16 a[32:47], v[180:183], v[192:195], 0
	v_mfma_f32_32x32x16_bf16 a[48:63], v[180:183], v[196:199], 0
	ds_read_b128 v[180:183], v49 offset:9216
	ds_read_b128 v[208:211], v45 offset:32
	ds_read_b128 v[212:215], v45 offset:4640
	v_lshl_add_u64 v[50:51], v[0:1], 0, s[34:35]
	global_load_dwordx4 v[52:55], v[50:51], off
	s_waitcnt lgkmcnt(3)
	v_mfma_f32_32x32x16_bf16 a[64:79], v[204:207], v[184:187], 0
	v_mfma_f32_32x32x16_bf16 a[80:95], v[204:207], v[188:191], 0
	v_mfma_f32_32x32x16_bf16 a[96:111], v[204:207], v[192:195], 0
	v_mfma_f32_32x32x16_bf16 a[112:127], v[204:207], v[196:199], 0
	ds_read_b128 v[204:207], v49 offset:13824
	ds_read_b128 v[216:219], v45 offset:9248
	ds_read_b128 v[220:223], v45 offset:13856
	v_lshl_add_u64 v[50:51], v[2:3], 0, s[34:35]
	s_or_b32 s2, s34, 0x10000
	s_mov_b32 s3, s35
	global_load_dwordx4 v[56:59], v[50:51], off
	s_waitcnt lgkmcnt(5)
	v_mfma_f32_32x32x16_bf16 a[128:143], v[180:183], v[184:187], 0
	v_mfma_f32_32x32x16_bf16 a[144:159], v[180:183], v[188:191], 0
	v_mfma_f32_32x32x16_bf16 a[160:175], v[180:183], v[192:195], 0
	v_mfma_f32_32x32x16_bf16 a[176:191], v[180:183], v[196:199], 0
	ds_read_b128 v[180:183], v49 offset:32
	v_lshl_add_u64 v[50:51], v[0:1], 0, s[2:3]
	global_load_dwordx4 v[60:63], v[50:51], off
	s_waitcnt lgkmcnt(3)
	v_mfma_f32_32x32x16_bf16 a[192:207], v[204:207], v[184:187], 0
	v_mfma_f32_32x32x16_bf16 a[208:223], v[204:207], v[188:191], 0
	v_mfma_f32_32x32x16_bf16 a[224:239], v[204:207], v[192:195], 0
	v_mfma_f32_32x32x16_bf16 a[240:255], v[204:207], v[196:199], 0
	ds_read_b128 v[204:207], v49 offset:4640
	v_lshl_add_u64 v[50:51], v[2:3], 0, s[2:3]
	s_or_b32 s2, s34, 0x20000
	global_load_dwordx4 v[64:67], v[50:51], off
	s_waitcnt vmcnt(16)
	ds_write_b128 v31, v[104:107]
	ds_write_b128 v32, v[108:111]
	ds_write_b128 v41, v[96:99]
	ds_write_b128 v42, v[100:103]
	s_waitcnt lgkmcnt(5)
	v_mfma_f32_32x32x16_bf16 a[0:15], v[180:183], v[208:211], a[0:15]
	v_mfma_f32_32x32x16_bf16 a[16:31], v[180:183], v[212:215], a[16:31]
	v_mfma_f32_32x32x16_bf16 a[32:47], v[180:183], v[216:219], a[32:47]
	v_mfma_f32_32x32x16_bf16 a[48:63], v[180:183], v[220:223], a[48:63]
	ds_read_b128 v[180:183], v49 offset:9248
	ds_read_b128 v[184:187], v45 offset:64
	ds_read_b128 v[188:191], v45 offset:4672
	v_lshl_add_u64 v[50:51], v[0:1], 0, s[2:3]
	global_load_dwordx4 v[68:71], v[50:51], off
	s_waitcnt lgkmcnt(7)
	v_mfma_f32_32x32x16_bf16 a[64:79], v[204:207], v[208:211], a[64:79]
	v_mfma_f32_32x32x16_bf16 a[80:95], v[204:207], v[212:215], a[80:95]
	v_mfma_f32_32x32x16_bf16 a[96:111], v[204:207], v[216:219], a[96:111]
	v_mfma_f32_32x32x16_bf16 a[112:127], v[204:207], v[220:223], a[112:127]
	ds_read_b128 v[204:207], v49 offset:13856
	ds_read_b128 v[192:195], v45 offset:9280
	ds_read_b128 v[196:199], v45 offset:13888
	v_lshl_add_u64 v[50:51], v[2:3], 0, s[2:3]
	s_or_b32 s2, s34, 0x30000
	global_load_dwordx4 v[72:75], v[50:51], off
	s_waitcnt lgkmcnt(5)
	v_mfma_f32_32x32x16_bf16 a[128:143], v[180:183], v[208:211], a[128:143]
	v_mfma_f32_32x32x16_bf16 a[144:159], v[180:183], v[212:215], a[144:159]
	v_mfma_f32_32x32x16_bf16 a[160:175], v[180:183], v[216:219], a[160:175]
	v_mfma_f32_32x32x16_bf16 a[176:191], v[180:183], v[220:223], a[176:191]
	ds_read_b128 v[180:183], v49 offset:64
	v_lshl_add_u64 v[50:51], v[0:1], 0, s[2:3]
	global_load_dwordx4 v[76:79], v[50:51], off
	s_waitcnt lgkmcnt(3)
	v_mfma_f32_32x32x16_bf16 a[192:207], v[204:207], v[208:211], a[192:207]
	v_mfma_f32_32x32x16_bf16 a[208:223], v[204:207], v[212:215], a[208:223]
	v_mfma_f32_32x32x16_bf16 a[224:239], v[204:207], v[216:219], a[224:239]
	v_mfma_f32_32x32x16_bf16 a[240:255], v[204:207], v[220:223], a[240:255]
	ds_read_b128 v[204:207], v49 offset:4672
	v_lshl_add_u64 v[50:51], v[2:3], 0, s[2:3]
	s_or_b32 s2, s34, 0x40000
	global_load_dwordx4 v[80:83], v[50:51], off
	s_waitcnt vmcnt(16)
	ds_write_b128 v37, v[116:119]
	ds_write_b128 v38, v[120:123]
	ds_write_b128 v39, v[128:131]
	ds_write_b128 v40, v[132:135]
	s_waitcnt lgkmcnt(5)
	v_mfma_f32_32x32x16_bf16 a[0:15], v[180:183], v[184:187], a[0:15]
	v_mfma_f32_32x32x16_bf16 a[16:31], v[180:183], v[188:191], a[16:31]
	v_mfma_f32_32x32x16_bf16 a[32:47], v[180:183], v[192:195], a[32:47]
	v_mfma_f32_32x32x16_bf16 a[48:63], v[180:183], v[196:199], a[48:63]
	ds_read_b128 v[180:183], v49 offset:9280
	ds_read_b128 v[208:211], v45 offset:96
	ds_read_b128 v[212:215], v45 offset:4704
	v_lshl_add_u64 v[50:51], v[0:1], 0, s[2:3]
	global_load_dwordx4 v[84:87], v[50:51], off
	s_waitcnt lgkmcnt(7)
	v_mfma_f32_32x32x16_bf16 a[64:79], v[204:207], v[184:187], a[64:79]
	v_mfma_f32_32x32x16_bf16 a[80:95], v[204:207], v[188:191], a[80:95]
	v_mfma_f32_32x32x16_bf16 a[96:111], v[204:207], v[192:195], a[96:111]
	v_mfma_f32_32x32x16_bf16 a[112:127], v[204:207], v[196:199], a[112:127]
	ds_read_b128 v[204:207], v49 offset:13888
	ds_read_b128 v[216:219], v45 offset:9312
	ds_read_b128 v[220:223], v45 offset:13920
	v_lshl_add_u64 v[50:51], v[2:3], 0, s[2:3]
	s_or_b32 s2, s34, 0x50000
	global_load_dwordx4 v[88:91], v[50:51], off
	s_waitcnt lgkmcnt(5)
; #define GLOAD(RA, RB, kt) { _Pragma("unroll") for (int i = 0; i < 8; ++i) { const int ia = (tail && i >= 4) ? i - 4 : i; \
;     RA[i] = *(const u32x4*)(abase + ((size_t)(32 * ia) * lda + (kt) * 64) * 2 + aoff); RB[i] = *(const u32x4*)(bbase + ((size_t)(32 * i) * K + (kt) * 64) * 2 + boff); } }
; #define LWRITE(RA, RB, buf) { char* as_ = lds + (buf) * 2 * G_TILE; char* bs_ = as_ + G_TILE; _Pragma("unroll") for (int i = 0; i < 8; ++i) { *(u32x4*)(as_ + (lrow + 32 * i) * GS_B + lch * 16) = RA[i]; *(u32x4*)(bs_ + (lrow + 32 * i) * GS_B + lch * 16) = RB[i]; } }
; template <int EPI>
; DEV void gemm_tile(CParams& p, int layer, const bf16_t* __restrict__ A, int lda, const bf16_t* __restrict__ Bt, int K, int m0, int n0, int nt, char* lds, const int swave) {
;     ...
;   GLOAD(ra0, rb0, 0); GLOAD(ra1, rb1, 1); LWRITE(ra0, rb0, 0); __syncthreads();
; #pragma unroll 1
;   for (int kt = 0; kt < nk; kt += 2) {
;     if (kt + 2 < nk) GLOAD(ra0, rb0, kt + 2);
;     COMPUTE(0, ra1, rb1, 1, true);
;     __syncthreads();
;     const bool more = kt + 2 < nk;
;     if (kt + 3 < nk) GLOAD(ra1, rb1, kt + 3);
;     COMPUTE(1, ra0, rb0, 0, more);
	v_mfma_f32_32x32x16_bf16 a[128:143], v[180:183], v[184:187], a[128:143]
	v_mfma_f32_32x32x16_bf16 a[144:159], v[180:183], v[188:191], a[144:159]
	v_mfma_f32_32x32x16_bf16 a[160:175], v[180:183], v[192:195], a[160:175]
	v_mfma_f32_32x32x16_bf16 a[176:191], v[180:183], v[196:199], a[176:191]
	ds_read_b128 v[180:183], v49 offset:96
	v_lshl_add_u64 v[50:51], v[0:1], 0, s[2:3]
	global_load_dwordx4 v[92:95], v[50:51], off
	s_waitcnt lgkmcnt(3)
	v_mfma_f32_32x32x16_bf16 a[192:207], v[204:207], v[184:187], a[192:207]
	v_mfma_f32_32x32x16_bf16 a[208:223], v[204:207], v[188:191], a[208:223]
	v_mfma_f32_32x32x16_bf16 a[224:239], v[204:207], v[192:195], a[224:239]
	v_mfma_f32_32x32x16_bf16 a[240:255], v[204:207], v[196:199], a[240:255]
	ds_read_b128 v[204:207], v49 offset:4704
	v_lshl_add_u64 v[50:51], v[2:3], 0, s[2:3]
	s_or_b32 s2, s34, 0x60000
	global_load_dwordx4 v[112:115], v[50:51], off
	s_waitcnt vmcnt(16)
	ds_write_b128 v33, v[136:139]
	ds_write_b128 v34, v[144:147]
	ds_write_b128 v35, v[148:151]
	ds_write_b128 v36, v[156:159]
	s_waitcnt lgkmcnt(5)
	v_mfma_f32_32x32x16_bf16 a[0:15], v[180:183], v[208:211], a[0:15]
	v_mfma_f32_32x32x16_bf16 a[16:31], v[180:183], v[212:215], a[16:31]
	v_mfma_f32_32x32x16_bf16 a[32:47], v[180:183], v[216:219], a[32:47]
	v_mfma_f32_32x32x16_bf16 a[48:63], v[180:183], v[220:223], a[48:63]
	ds_read_b128 v[180:183], v49 offset:9312
	v_lshl_add_u64 v[50:51], v[0:1], 0, s[2:3]
	global_load_dwordx4 v[124:127], v[50:51], off
	s_waitcnt lgkmcnt(5)
	v_mfma_f32_32x32x16_bf16 a[64:79], v[204:207], v[208:211], a[64:79]
	v_mfma_f32_32x32x16_bf16 a[80:95], v[204:207], v[212:215], a[80:95]
	v_mfma_f32_32x32x16_bf16 a[96:111], v[204:207], v[216:219], a[96:111]
	v_mfma_f32_32x32x16_bf16 a[112:127], v[204:207], v[220:223], a[112:127]
	ds_read_b128 v[204:207], v49 offset:13920
	v_lshl_add_u64 v[50:51], v[2:3], 0, s[2:3]
	s_or_b32 s34, s34, 0x70000
	global_load_dwordx4 v[140:143], v[50:51], off
	s_waitcnt lgkmcnt(1)
	v_mfma_f32_32x32x16_bf16 a[128:143], v[180:183], v[208:211], a[128:143]
	v_mfma_f32_32x32x16_bf16 a[144:159], v[180:183], v[212:215], a[144:159]
	v_mfma_f32_32x32x16_bf16 a[160:175], v[180:183], v[216:219], a[160:175]
	v_mfma_f32_32x32x16_bf16 a[176:191], v[180:183], v[220:223], a[176:191]
	v_lshl_add_u64 v[50:51], v[0:1], 0, s[34:35]
	global_load_dwordx4 v[152:155], v[50:51], off
	s_waitcnt lgkmcnt(0)
	v_mfma_f32_32x32x16_bf16 a[192:207], v[204:207], v[208:211], a[192:207]
	v_mfma_f32_32x32x16_bf16 a[208:223], v[204:207], v[212:215], a[208:223]
	v_mfma_f32_32x32x16_bf16 a[224:239], v[204:207], v[216:219], a[224:239]
	v_mfma_f32_32x32x16_bf16 a[240:255], v[204:207], v[220:223], a[240:255]
	v_lshl_add_u64 v[50:51], v[2:3], 0, s[34:35]
	global_load_dwordx4 v[172:175], v[50:51], off
	s_waitcnt vmcnt(16)
	ds_write_b128 v43, v[160:163]
	ds_write_b128 v44, v[164:167]
	ds_write_b128 v46, v[168:171]
	ds_write_b128 v47, v[176:179]
	s_branch .LBB0_937
.Lzi_i3:
	ds_read_b128 v[184:187], v45
	ds_read_b128 v[188:191], v45 offset:4608
	ds_read_b128 v[192:195], v45 offset:9216
	ds_read_b128 v[196:199], v45 offset:13824
	ds_read_b128 v[180:183], v49
	ds_read_b128 v[204:207], v49 offset:4608
	s_waitcnt lgkmcnt(1)
	v_mfma_f32_32x32x16_bf16 a[0:15], v[180:183], v[184:187], a[0:15]
	v_mfma_f32_32x32x16_bf16 a[16:31], v[180:183], v[188:191], a[16:31]
	v_mfma_f32_32x32x16_bf16 a[32:47], v[180:183], v[192:195], a[32:47]
	v_mfma_f32_32x32x16_bf16 a[48:63], v[180:183], v[196:199], a[48:63]
	ds_read_b128 v[180:183], v49 offset:9216
	ds_read_b128 v[208:211], v45 offset:32
	ds_read_b128 v[212:215], v45 offset:4640
	v_lshl_add_u64 v[50:51], v[0:1], 0, s[34:35]
	global_load_dwordx4 v[52:55], v[50:51], off
	s_waitcnt lgkmcnt(3)
	v_mfma_f32_32x32x16_bf16 a[64:79], v[204:207], v[184:187], a[64:79]
	v_mfma_f32_32x32x16_bf16 a[80:95], v[204:207], v[188:191], a[80:95]
	v_mfma_f32_32x32x16_bf16 a[96:111], v[204:207], v[192:195], a[96:111]
	v_mfma_f32_32x32x16_bf16 a[112:127], v[204:207], v[196:199], a[112:127]
	ds_read_b128 v[204:207], v49 offset:13824
	ds_read_b128 v[216:219], v45 offset:9248
	ds_read_b128 v[220:223], v45 offset:13856
	v_lshl_add_u64 v[50:51], v[2:3], 0, s[34:35]
	s_or_b32 s2, s34, 0x10000
	s_mov_b32 s3, s35
	global_load_dwordx4 v[56:59], v[50:51], off
	s_waitcnt lgkmcnt(5)
	v_mfma_f32_32x32x16_bf16 a[128:143], v[180:183], v[184:187], a[128:143]
	v_mfma_f32_32x32x16_bf16 a[144:159], v[180:183], v[188:191], a[144:159]
	v_mfma_f32_32x32x16_bf16 a[160:175], v[180:183], v[192:195], a[160:175]
	v_mfma_f32_32x32x16_bf16 a[176:191], v[180:183], v[196:199], a[176:191]
	ds_read_b128 v[180:183], v49 offset:32
	v_lshl_add_u64 v[50:51], v[0:1], 0, s[2:3]
	global_load_dwordx4 v[60:63], v[50:51], off
	s_waitcnt lgkmcnt(3)
	v_mfma_f32_32x32x16_bf16 a[192:207], v[204:207], v[184:187], a[192:207]
	v_mfma_f32_32x32x16_bf16 a[208:223], v[204:207], v[188:191], a[208:223]
	v_mfma_f32_32x32x16_bf16 a[224:239], v[204:207], v[192:195], a[224:239]
	v_mfma_f32_32x32x16_bf16 a[240:255], v[204:207], v[196:199], a[240:255]
	ds_read_b128 v[204:207], v49 offset:4640
	v_lshl_add_u64 v[50:51], v[2:3], 0, s[2:3]
	s_or_b32 s2, s34, 0x20000
	global_load_dwordx4 v[64:67], v[50:51], off
	s_waitcnt vmcnt(16)
	ds_write_b128 v31, v[104:107]
	ds_write_b128 v32, v[108:111]
	ds_write_b128 v41, v[96:99]
	ds_write_b128 v42, v[100:103]
	s_waitcnt lgkmcnt(5)
	v_mfma_f32_32x32x16_bf16 a[0:15], v[180:183], v[208:211], a[0:15]
	v_mfma_f32_32x32x16_bf16 a[16:31], v[180:183], v[212:215], a[16:31]
	v_mfma_f32_32x32x16_bf16 a[32:47], v[180:183], v[216:219], a[32:47]
	v_mfma_f32_32x32x16_bf16 a[48:63], v[180:183], v[220:223], a[48:63]
	ds_read_b128 v[180:183], v49 offset:9248
	ds_read_b128 v[184:187], v45 offset:64
	ds_read_b128 v[188:191], v45 offset:4672
	v_lshl_add_u64 v[50:51], v[0:1], 0, s[2:3]
	global_load_dwordx4 v[68:71], v[50:51], off
	s_waitcnt lgkmcnt(7)
; #define GLOAD(RA, RB, kt) { _Pragma("unroll") for (int i = 0; i < 8; ++i) { const int ia = (tail && i >= 4) ? i - 4 : i; \
;     RA[i] = *(const u32x4*)(abase + ((size_t)(32 * ia) * lda + (kt) * 64) * 2 + aoff); RB[i] = *(const u32x4*)(bbase + ((size_t)(32 * i) * K + (kt) * 64) * 2 + boff); } }
; #define LWRITE(RA, RB, buf) { char* as_ = lds + (buf) * 2 * G_TILE; char* bs_ = as_ + G_TILE; _Pragma("unroll") for (int i = 0; i < 8; ++i) { *(u32x4*)(as_ + (lrow + 32 * i) * GS_B + lch * 16) = RA[i]; *(u32x4*)(bs_ + (lrow + 32 * i) * GS_B + lch * 16) = RB[i]; } }
; template <int EPI>
; DEV void gemm_tile(CParams& p, int layer, const bf16_t* __restrict__ A, int lda, const bf16_t* __restrict__ Bt, int K, int m0, int n0, int nt, char* lds, const int swave) {
;     ...
;   GLOAD(ra0, rb0, 0); GLOAD(ra1, rb1, 1); LWRITE(ra0, rb0, 0); __syncthreads();
; #pragma unroll 1
;   for (int kt = 0; kt < nk; kt += 2) {
;     if (kt + 2 < nk) GLOAD(ra0, rb0, kt + 2);
;     COMPUTE(0, ra1, rb1, 1, true);
;     __syncthreads();
;     const bool more = kt + 2 < nk;
;     if (kt + 3 < nk) GLOAD(ra1, rb1, kt + 3);
;     COMPUTE(1, ra0, rb0, 0, more);
	v_mfma_f32_32x32x16_bf16 a[64:79], v[204:207], v[208:211], a[64:79]
	v_mfma_f32_32x32x16_bf16 a[80:95], v[204:207], v[212:215], a[80:95]
	v_mfma_f32_32x32x16_bf16 a[96:111], v[204:207], v[216:219], a[96:111]
	v_mfma_f32_32x32x16_bf16 a[112:127], v[204:207], v[220:223], a[112:127]
	ds_read_b128 v[204:207], v49 offset:13856
	ds_read_b128 v[192:195], v45 offset:9280
	ds_read_b128 v[196:199], v45 offset:13888
	v_lshl_add_u64 v[50:51], v[2:3], 0, s[2:3]
	s_or_b32 s2, s34, 0x30000
	global_load_dwordx4 v[72:75], v[50:51], off
	s_waitcnt lgkmcnt(5)
	v_mfma_f32_32x32x16_bf16 a[128:143], v[180:183], v[208:211], a[128:143]
	v_mfma_f32_32x32x16_bf16 a[144:159], v[180:183], v[212:215], a[144:159]
	v_mfma_f32_32x32x16_bf16 a[160:175], v[180:183], v[216:219], a[160:175]
	v_mfma_f32_32x32x16_bf16 a[176:191], v[180:183], v[220:223], a[176:191]
	ds_read_b128 v[180:183], v49 offset:64
	v_lshl_add_u64 v[50:51], v[0:1], 0, s[2:3]
	global_load_dwordx4 v[76:79], v[50:51], off
	s_waitcnt lgkmcnt(3)
	v_mfma_f32_32x32x16_bf16 a[192:207], v[204:207], v[208:211], a[192:207]
	v_mfma_f32_32x32x16_bf16 a[208:223], v[204:207], v[212:215], a[208:223]
	v_mfma_f32_32x32x16_bf16 a[224:239], v[204:207], v[216:219], a[224:239]
	v_mfma_f32_32x32x16_bf16 a[240:255], v[204:207], v[220:223], a[240:255]
	ds_read_b128 v[204:207], v49 offset:4672
	v_lshl_add_u64 v[50:51], v[2:3], 0, s[2:3]
	s_or_b32 s2, s34, 0x40000
	global_load_dwordx4 v[80:83], v[50:51], off
	s_waitcnt vmcnt(16)
	ds_write_b128 v37, v[116:119]
	ds_write_b128 v38, v[120:123]
	ds_write_b128 v39, v[128:131]
	ds_write_b128 v40, v[132:135]
	s_waitcnt lgkmcnt(5)
	v_mfma_f32_32x32x16_bf16 a[0:15], v[180:183], v[184:187], a[0:15]
	v_mfma_f32_32x32x16_bf16 a[16:31], v[180:183], v[188:191], a[16:31]
	v_mfma_f32_32x32x16_bf16 a[32:47], v[180:183], v[192:195], a[32:47]
	v_mfma_f32_32x32x16_bf16 a[48:63], v[180:183], v[196:199], a[48:63]
	ds_read_b128 v[180:183], v49 offset:9280
	ds_read_b128 v[208:211], v45 offset:96
	ds_read_b128 v[212:215], v45 offset:4704
	v_lshl_add_u64 v[50:51], v[0:1], 0, s[2:3]
	global_load_dwordx4 v[84:87], v[50:51], off
	s_waitcnt lgkmcnt(7)
	v_mfma_f32_32x32x16_bf16 a[64:79], v[204:207], v[184:187], a[64:79]
	v_mfma_f32_32x32x16_bf16 a[80:95], v[204:207], v[188:191], a[80:95]
	v_mfma_f32_32x32x16_bf16 a[96:111], v[204:207], v[192:195], a[96:111]
	v_mfma_f32_32x32x16_bf16 a[112:127], v[204:207], v[196:199], a[112:127]
	ds_read_b128 v[204:207], v49 offset:13888
	ds_read_b128 v[216:219], v45 offset:9312
	ds_read_b128 v[220:223], v45 offset:13920
	v_lshl_add_u64 v[50:51], v[2:3], 0, s[2:3]
	s_or_b32 s2, s34, 0x50000
	global_load_dwordx4 v[88:91], v[50:51], off
	s_waitcnt lgkmcnt(5)
	v_mfma_f32_32x32x16_bf16 a[128:143], v[180:183], v[184:187], a[128:143]
	v_mfma_f32_32x32x16_bf16 a[144:159], v[180:183], v[188:191], a[144:159]
	v_mfma_f32_32x32x16_bf16 a[160:175], v[180:183], v[192:195], a[160:175]
	v_mfma_f32_32x32x16_bf16 a[176:191], v[180:183], v[196:199], a[176:191]
	ds_read_b128 v[180:183], v49 offset:96
	v_lshl_add_u64 v[50:51], v[0:1], 0, s[2:3]
	global_load_dwordx4 v[92:95], v[50:51], off
	s_waitcnt lgkmcnt(3)
	v_mfma_f32_32x32x16_bf16 a[192:207], v[204:207], v[184:187], a[192:207]
	v_mfma_f32_32x32x16_bf16 a[208:223], v[204:207], v[188:191], a[208:223]
	v_mfma_f32_32x32x16_bf16 a[224:239], v[204:207], v[192:195], a[224:239]
	v_mfma_f32_32x32x16_bf16 a[240:255], v[204:207], v[196:199], a[240:255]
	ds_read_b128 v[204:207], v49 offset:4704
	v_lshl_add_u64 v[50:51], v[2:3], 0, s[2:3]
	s_or_b32 s2, s34, 0x60000
	global_load_dwordx4 v[112:115], v[50:51], off
	s_waitcnt vmcnt(16)
	ds_write_b128 v33, v[136:139]
	ds_write_b128 v34, v[144:147]
	ds_write_b128 v35, v[148:151]
	ds_write_b128 v36, v[156:159]
	s_waitcnt lgkmcnt(5)
	v_mfma_f32_32x32x16_bf16 a[0:15], v[180:183], v[208:211], a[0:15]
	v_mfma_f32_32x32x16_bf16 a[16:31], v[180:183], v[212:215], a[16:31]
	v_mfma_f32_32x32x16_bf16 a[32:47], v[180:183], v[216:219], a[32:47]
	v_mfma_f32_32x32x16_bf16 a[48:63], v[180:183], v[220:223], a[48:63]
	ds_read_b128 v[180:183], v49 offset:9312
	v_lshl_add_u64 v[50:51], v[0:1], 0, s[2:3]
	global_load_dwordx4 v[124:127], v[50:51], off
	s_waitcnt lgkmcnt(5)
	v_mfma_f32_32x32x16_bf16 a[64:79], v[204:207], v[208:211], a[64:79]
	v_mfma_f32_32x32x16_bf16 a[80:95], v[204:207], v[212:215], a[80:95]
	v_mfma_f32_32x32x16_bf16 a[96:111], v[204:207], v[216:219], a[96:111]
	v_mfma_f32_32x32x16_bf16 a[112:127], v[204:207], v[220:223], a[112:127]
	ds_read_b128 v[204:207], v49 offset:13920
	v_lshl_add_u64 v[50:51], v[2:3], 0, s[2:3]
	s_or_b32 s34, s34, 0x70000
	global_load_dwordx4 v[140:143], v[50:51], off
	s_waitcnt lgkmcnt(1)
	v_mfma_f32_32x32x16_bf16 a[128:143], v[180:183], v[208:211], a[128:143]
	v_mfma_f32_32x32x16_bf16 a[144:159], v[180:183], v[212:215], a[144:159]
	v_mfma_f32_32x32x16_bf16 a[160:175], v[180:183], v[216:219], a[160:175]
	v_mfma_f32_32x32x16_bf16 a[176:191], v[180:183], v[220:223], a[176:191]
	v_lshl_add_u64 v[50:51], v[0:1], 0, s[34:35]
	global_load_dwordx4 v[152:155], v[50:51], off
	s_waitcnt lgkmcnt(0)
	v_mfma_f32_32x32x16_bf16 a[192:207], v[204:207], v[208:211], a[192:207]
	v_mfma_f32_32x32x16_bf16 a[208:223], v[204:207], v[212:215], a[208:223]
	v_mfma_f32_32x32x16_bf16 a[224:239], v[204:207], v[216:219], a[224:239]
	v_mfma_f32_32x32x16_bf16 a[240:255], v[204:207], v[220:223], a[240:255]
	v_lshl_add_u64 v[50:51], v[2:3], 0, s[34:35]
	global_load_dwordx4 v[172:175], v[50:51], off
	s_waitcnt vmcnt(16)
	ds_write_b128 v43, v[160:163]
	ds_write_b128 v44, v[164:167]
	ds_write_b128 v46, v[168:171]
	ds_write_b128 v47, v[176:179]

; #define GLOAD(RA, RB, kt) { _Pragma("unroll") for (int i = 0; i < 8; ++i) { const int ia = (tail && i >= 4) ? i - 4 : i; \
;     RA[i] = *(const u32x4*)(abase + ((size_t)(32 * ia) * lda + (kt) * 64) * 2 + aoff); RB[i] = *(const u32x4*)(bbase + ((size_t)(32 * i) * K + (kt) * 64) * 2 + boff); } }
; #define LWRITE(RA, RB, buf) { char* as_ = lds + (buf) * 2 * G_TILE; char* bs_ = as_ + G_TILE; _Pragma("unroll") for (int i = 0; i < 8; ++i) { *(u32x4*)(as_ + (lrow + 32 * i) * GS_B + lch * 16) = RA[i]; *(u32x4*)(bs_ + (lrow + 32 * i) * GS_B + lch * 16) = RB[i]; } }
; template <int EPI>
; DEV void gemm_tile(CParams& p, int layer, const bf16_t* __restrict__ A, int lda, const bf16_t* __restrict__ Bt, int K, int m0, int n0, int nt, char* lds, const int swave) {
;     ...
;   GLOAD(ra0, rb0, 0); GLOAD(ra1, rb1, 1); LWRITE(ra0, rb0, 0); __syncthreads();
; #pragma unroll 1
;   for (int kt = 0; kt < nk; kt += 2) {
;     if (kt + 2 < nk) GLOAD(ra0, rb0, kt + 2);
;     COMPUTE(0, ra1, rb1, 1, true);
;     __syncthreads();
;     const bool more = kt + 2 < nk;
;     if (kt + 3 < nk) GLOAD(ra1, rb1, kt + 3);
;     COMPUTE(1, ra0, rb0, 0, more);
.LBB0_939:
	v_add_u32_e32 v224, 0x1b000, v29
	v_add_u32_e32 v225, 0x12000, v45
	s_andn2_b64 vcc, exec, s[60:61]
	s_cbranch_vccnz .Lpg_i3_nomore
	ds_read_b128 v[184:187], v225
	ds_read_b128 v[188:191], v225 offset:4608
	ds_read_b128 v[192:195], v225 offset:9216
	ds_read_b128 v[196:199], v225 offset:13824
	ds_read_b128 v[180:183], v224
	ds_read_b128 v[204:207], v224 offset:4608
	s_waitcnt lgkmcnt(1)
	v_mfma_f32_32x32x16_bf16 a[0:15], v[180:183], v[184:187], a[0:15]
	v_mfma_f32_32x32x16_bf16 a[16:31], v[180:183], v[188:191], a[16:31]
	v_mfma_f32_32x32x16_bf16 a[32:47], v[180:183], v[192:195], a[32:47]
	v_mfma_f32_32x32x16_bf16 a[48:63], v[180:183], v[196:199], a[48:63]
	ds_read_b128 v[180:183], v224 offset:9216
	ds_read_b128 v[208:211], v225 offset:32
	ds_read_b128 v[212:215], v225 offset:4640
	s_lshl_b32 s34, s42, 7
	v_lshl_add_u64 v[50:51], v[0:1], 0, s[34:35]
	v_lshl_add_u64 v[96:97], v[2:3], 0, s[34:35]
	global_load_dwordx4 v[104:107], v[50:51], off offset:384
	s_waitcnt lgkmcnt(3)
	v_mfma_f32_32x32x16_bf16 a[64:79], v[204:207], v[184:187], a[64:79]
	v_mfma_f32_32x32x16_bf16 a[80:95], v[204:207], v[188:191], a[80:95]
	v_mfma_f32_32x32x16_bf16 a[96:111], v[204:207], v[192:195], a[96:111]
	v_mfma_f32_32x32x16_bf16 a[112:127], v[204:207], v[196:199], a[112:127]
	ds_read_b128 v[204:207], v224 offset:13824
	ds_read_b128 v[216:219], v225 offset:9248
	ds_read_b128 v[220:223], v225 offset:13856
	global_load_dwordx4 v[108:111], v[96:97], off offset:384
	s_waitcnt lgkmcnt(5)
	v_mfma_f32_32x32x16_bf16 a[128:143], v[180:183], v[184:187], a[128:143]
	v_mfma_f32_32x32x16_bf16 a[144:159], v[180:183], v[188:191], a[144:159]
	v_mfma_f32_32x32x16_bf16 a[160:175], v[180:183], v[192:195], a[160:175]
	v_mfma_f32_32x32x16_bf16 a[176:191], v[180:183], v[196:199], a[176:191]
	ds_read_b128 v[180:183], v224 offset:32
	v_add_co_u32_e32 v50, vcc, 0x10000, v50
	v_lshl_add_u64 v[120:121], v[6:7], 0, s[34:35]
	v_addc_co_u32_e32 v51, vcc, 0, v51, vcc
	v_add_co_u32_e32 v100, vcc, 0x10000, v96
	v_lshl_add_u64 v[132:133], v[10:11], 0, s[34:35]
	v_addc_co_u32_e32 v101, vcc, 0, v97, vcc
	global_load_dwordx4 v[96:99], v[50:51], off offset:384
	s_waitcnt lgkmcnt(3)
	v_mfma_f32_32x32x16_bf16 a[192:207], v[204:207], v[184:187], a[192:207]
	v_mfma_f32_32x32x16_bf16 a[208:223], v[204:207], v[188:191], a[208:223]
	v_mfma_f32_32x32x16_bf16 a[224:239], v[204:207], v[192:195], a[224:239]
	v_mfma_f32_32x32x16_bf16 a[240:255], v[204:207], v[196:199], a[240:255]
	ds_read_b128 v[204:207], v224 offset:4640
	s_nop 0
	global_load_dwordx4 v[100:103], v[100:101], off offset:384
	s_waitcnt vmcnt(16)
	ds_write_b128 v30, v[52:55]
	ds_write_b128 v30, v[56:59] offset:36864
	ds_write_b128 v30, v[60:63] offset:4608
	ds_write_b128 v30, v[64:67] offset:41472
	s_waitcnt lgkmcnt(5)
	v_mfma_f32_32x32x16_bf16 a[0:15], v[180:183], v[208:211], a[0:15]
	v_mfma_f32_32x32x16_bf16 a[16:31], v[180:183], v[212:215], a[16:31]
	v_mfma_f32_32x32x16_bf16 a[32:47], v[180:183], v[216:219], a[32:47]
	v_mfma_f32_32x32x16_bf16 a[48:63], v[180:183], v[220:223], a[48:63]
	ds_read_b128 v[180:183], v224 offset:9248
	ds_read_b128 v[184:187], v225 offset:64
	ds_read_b128 v[188:191], v225 offset:4672
	v_lshl_add_u64 v[50:51], v[4:5], 0, s[34:35]
	global_load_dwordx4 v[116:119], v[50:51], off offset:384
	s_waitcnt lgkmcnt(7)
	v_mfma_f32_32x32x16_bf16 a[64:79], v[204:207], v[208:211], a[64:79]
	v_mfma_f32_32x32x16_bf16 a[80:95], v[204:207], v[212:215], a[80:95]
	v_mfma_f32_32x32x16_bf16 a[96:111], v[204:207], v[216:219], a[96:111]
	v_mfma_f32_32x32x16_bf16 a[112:127], v[204:207], v[220:223], a[112:127]
	ds_read_b128 v[204:207], v224 offset:13856
	ds_read_b128 v[192:195], v225 offset:9280
	ds_read_b128 v[196:199], v225 offset:13888
	s_nop 0
	global_load_dwordx4 v[120:123], v[120:121], off offset:384
	s_waitcnt lgkmcnt(5)
	v_mfma_f32_32x32x16_bf16 a[128:143], v[180:183], v[208:211], a[128:143]
	v_mfma_f32_32x32x16_bf16 a[144:159], v[180:183], v[212:215], a[144:159]
	v_mfma_f32_32x32x16_bf16 a[160:175], v[180:183], v[216:219], a[160:175]
	v_mfma_f32_32x32x16_bf16 a[176:191], v[180:183], v[220:223], a[176:191]
	ds_read_b128 v[180:183], v224 offset:64
	v_lshl_add_u64 v[50:51], v[8:9], 0, s[34:35]
	global_load_dwordx4 v[128:131], v[50:51], off offset:384
	s_waitcnt lgkmcnt(3)
	v_mfma_f32_32x32x16_bf16 a[192:207], v[204:207], v[208:211], a[192:207]
	v_mfma_f32_32x32x16_bf16 a[208:223], v[204:207], v[212:215], a[208:223]
	v_mfma_f32_32x32x16_bf16 a[224:239], v[204:207], v[216:219], a[224:239]
	v_mfma_f32_32x32x16_bf16 a[240:255], v[204:207], v[220:223], a[240:255]
	ds_read_b128 v[204:207], v224 offset:4672
	s_nop 0
	global_load_dwordx4 v[132:135], v[132:133], off offset:384
	s_waitcnt vmcnt(16)
; #define GLOAD(RA, RB, kt) { _Pragma("unroll") for (int i = 0; i < 8; ++i) { const int ia = (tail && i >= 4) ? i - 4 : i; \
;     RA[i] = *(const u32x4*)(abase + ((size_t)(32 * ia) * lda + (kt) * 64) * 2 + aoff); RB[i] = *(const u32x4*)(bbase + ((size_t)(32 * i) * K + (kt) * 64) * 2 + boff); } }
; #define LWRITE(RA, RB, buf) { char* as_ = lds + (buf) * 2 * G_TILE; char* bs_ = as_ + G_TILE; _Pragma("unroll") for (int i = 0; i < 8; ++i) { *(u32x4*)(as_ + (lrow + 32 * i) * GS_B + lch * 16) = RA[i]; *(u32x4*)(bs_ + (lrow + 32 * i) * GS_B + lch * 16) = RB[i]; } }
; template <int EPI>
; DEV void gemm_tile(CParams& p, int layer, const bf16_t* __restrict__ A, int lda, const bf16_t* __restrict__ Bt, int K, int m0, int n0, int nt, char* lds, const int swave) {
;     ...
;   GLOAD(ra0, rb0, 0); GLOAD(ra1, rb1, 1); LWRITE(ra0, rb0, 0); __syncthreads();
; #pragma unroll 1
;   for (int kt = 0; kt < nk; kt += 2) {
;     if (kt + 2 < nk) GLOAD(ra0, rb0, kt + 2);
;     COMPUTE(0, ra1, rb1, 1, true);
;     __syncthreads();
;     const bool more = kt + 2 < nk;
;     if (kt + 3 < nk) GLOAD(ra1, rb1, kt + 3);
;     COMPUTE(1, ra0, rb0, 0, more);
	ds_write_b128 v30, v[68:71] offset:9216
	ds_write_b128 v30, v[72:75] offset:46080
	ds_write_b128 v30, v[76:79] offset:13824
	ds_write_b128 v30, v[80:83] offset:50688
	s_waitcnt lgkmcnt(5)
	v_mfma_f32_32x32x16_bf16 a[0:15], v[180:183], v[184:187], a[0:15]
	v_mfma_f32_32x32x16_bf16 a[16:31], v[180:183], v[188:191], a[16:31]
	v_mfma_f32_32x32x16_bf16 a[32:47], v[180:183], v[192:195], a[32:47]
	v_mfma_f32_32x32x16_bf16 a[48:63], v[180:183], v[196:199], a[48:63]
	ds_read_b128 v[180:183], v224 offset:9280
	ds_read_b128 v[208:211], v225 offset:96
	ds_read_b128 v[212:215], v225 offset:4704
	v_lshl_add_u64 v[50:51], v[12:13], 0, s[34:35]
	v_lshl_add_u64 v[144:145], v[14:15], 0, s[34:35]
	global_load_dwordx4 v[136:139], v[50:51], off offset:384
	s_waitcnt lgkmcnt(7)
	v_mfma_f32_32x32x16_bf16 a[64:79], v[204:207], v[184:187], a[64:79]
	v_mfma_f32_32x32x16_bf16 a[80:95], v[204:207], v[188:191], a[80:95]
	v_mfma_f32_32x32x16_bf16 a[96:111], v[204:207], v[192:195], a[96:111]
	v_mfma_f32_32x32x16_bf16 a[112:127], v[204:207], v[196:199], a[112:127]
	ds_read_b128 v[204:207], v224 offset:13888
	ds_read_b128 v[216:219], v225 offset:9312
	ds_read_b128 v[220:223], v225 offset:13920
	s_nop 0
	global_load_dwordx4 v[144:147], v[144:145], off offset:384
	s_waitcnt lgkmcnt(5)
	v_mfma_f32_32x32x16_bf16 a[128:143], v[180:183], v[184:187], a[128:143]
	v_mfma_f32_32x32x16_bf16 a[144:159], v[180:183], v[188:191], a[144:159]
	v_mfma_f32_32x32x16_bf16 a[160:175], v[180:183], v[192:195], a[160:175]
	v_mfma_f32_32x32x16_bf16 a[176:191], v[180:183], v[196:199], a[176:191]
	ds_read_b128 v[180:183], v224 offset:96
	v_lshl_add_u64 v[50:51], v[16:17], 0, s[34:35]
	v_lshl_add_u64 v[156:157], v[18:19], 0, s[34:35]
	global_load_dwordx4 v[148:151], v[50:51], off offset:384
	s_waitcnt lgkmcnt(3)
	v_mfma_f32_32x32x16_bf16 a[192:207], v[204:207], v[184:187], a[192:207]
	v_mfma_f32_32x32x16_bf16 a[208:223], v[204:207], v[188:191], a[208:223]
	v_mfma_f32_32x32x16_bf16 a[224:239], v[204:207], v[192:195], a[224:239]
	v_mfma_f32_32x32x16_bf16 a[240:255], v[204:207], v[196:199], a[240:255]
	ds_read_b128 v[204:207], v224 offset:4704
	s_nop 0
	global_load_dwordx4 v[156:159], v[156:157], off offset:384
	s_waitcnt vmcnt(16)
	ds_write_b128 v30, v[84:87] offset:18432
	ds_write_b128 v30, v[88:91] offset:55296
	ds_write_b128 v30, v[92:95] offset:23040
	ds_write_b128 v30, v[112:115] offset:59904
	s_waitcnt lgkmcnt(5)
	v_mfma_f32_32x32x16_bf16 a[0:15], v[180:183], v[208:211], a[0:15]
	v_mfma_f32_32x32x16_bf16 a[16:31], v[180:183], v[212:215], a[16:31]
	v_mfma_f32_32x32x16_bf16 a[32:47], v[180:183], v[216:219], a[32:47]
	v_mfma_f32_32x32x16_bf16 a[48:63], v[180:183], v[220:223], a[48:63]
	ds_read_b128 v[180:183], v224 offset:9312
	v_lshl_add_u64 v[50:51], v[20:21], 0, s[34:35]
	v_lshl_add_u64 v[164:165], v[22:23], 0, s[34:35]
	global_load_dwordx4 v[160:163], v[50:51], off offset:384
	s_waitcnt lgkmcnt(5)
	v_mfma_f32_32x32x16_bf16 a[64:79], v[204:207], v[208:211], a[64:79]
	v_mfma_f32_32x32x16_bf16 a[80:95], v[204:207], v[212:215], a[80:95]
	v_mfma_f32_32x32x16_bf16 a[96:111], v[204:207], v[216:219], a[96:111]
	v_mfma_f32_32x32x16_bf16 a[112:127], v[204:207], v[220:223], a[112:127]
	ds_read_b128 v[204:207], v224 offset:13920
	s_nop 0
	global_load_dwordx4 v[164:167], v[164:165], off offset:384
	s_waitcnt lgkmcnt(1)
	v_mfma_f32_32x32x16_bf16 a[128:143], v[180:183], v[208:211], a[128:143]
	v_mfma_f32_32x32x16_bf16 a[144:159], v[180:183], v[212:215], a[144:159]
	v_mfma_f32_32x32x16_bf16 a[160:175], v[180:183], v[216:219], a[160:175]
	v_mfma_f32_32x32x16_bf16 a[176:191], v[180:183], v[220:223], a[176:191]
	v_lshl_add_u64 v[50:51], v[24:25], 0, s[34:35]
	v_lshl_add_u64 v[176:177], v[26:27], 0, s[34:35]
	global_load_dwordx4 v[168:171], v[50:51], off offset:384
	s_waitcnt lgkmcnt(0)
	v_mfma_f32_32x32x16_bf16 a[192:207], v[204:207], v[208:211], a[192:207]
	v_mfma_f32_32x32x16_bf16 a[208:223], v[204:207], v[212:215], a[208:223]
	v_mfma_f32_32x32x16_bf16 a[224:239], v[204:207], v[216:219], a[224:239]
	v_mfma_f32_32x32x16_bf16 a[240:255], v[204:207], v[220:223], a[240:255]
	s_nop 0
	global_load_dwordx4 v[176:179], v[176:177], off offset:384
	s_waitcnt vmcnt(16)
	ds_write_b128 v30, v[124:127] offset:27648
	ds_write_b128 v30, v[140:143] offset:64512
	ds_write_b128 v30, v[152:155] offset:32256
	ds_write_b128 v48, v[172:175]
	s_branch .LBB0_918
